# v49 + removed 16 provably redundant s_waitcnt lgkmcnt(0) after the phase barrier in the GEMM K-loops (no LDS op between the pre-barrier wait and this one)
# speedup vs baseline: 1.0045x; 1.0045x over previous
; #define PG8_STAGE(bufoff, gbase, voff) do { _Pragma("unroll") for (int _i = 0; _i < 2; ++_i) \
;         __builtin_amdgcn_global_load_lds((const unsigned*)((const char*)(gbase) + (voff)[_i]), (LAS unsigned*)(lds + (bufoff) + ldsw + _i * 8192), 16, 0, 0); } while (0)
; #define PG8_LDA(dst, b, h) do { _Pragma("unroll") for (int m = 0; m < 4; ++m) _Pragma("unroll") for (int k = 0; k < 2; ++k) dst[m][k] = *(const LAS bf16x8*)(lds + PG8_SA(b, h) + aoff + m * 2048 + k * 1024); } while (0)
; #define PG8_LDB(dst, b, h) do { _Pragma("unroll") for (int n = 0; n < 2; ++n) _Pragma("unroll") for (int k = 0; k < 2; ++k) dst[n][k] = *(const LAS bf16x8*)(lds + PG8_SB(b, h) + boff + n * 2048 + k * 1024); } while (0)
; #define PG8_MMA(ai, bj, At, Bt) do { __builtin_amdgcn_s_setprio(1); _Pragma("unroll") for (int m = 0; m < 4; ++m) _Pragma("unroll") for (int n = 0; n < 2; ++n) _Pragma("unroll") for (int k = 0; k < 2; ++k) \
;         acc[ai][bj][m][n] = __builtin_amdgcn_mfma_f32_16x16x32_bf16(Bt[n][k], At[m][k], acc[ai][bj][m][n], 0, 0, 0); __builtin_amdgcn_s_setprio(0); } while (0)
; #define PG8_BAR __builtin_amdgcn_s_barrier()
; template <class Epi>
; __device__ __forceinline__ void gemm_phase(LAS unsigned char* lds, const Gemm g, const StaticOrder& S, const Epi& E, const int tid) {
;     ...
;         const char* nA = has_next ? (const char*)g.A + (size_t)nxt.pm * tstepA : cA; const char* nB = has_next ? (const char*)g.Bt + (size_t)nxt.pn * tstepB : cB;
;         for (int t = 0; t < nt; t += 2) {
;             const bool last = (t == nt - 2);
;             const char* a1 = cA + (size_t)(t + 1) * kstep + ((t + 1) >= 8 ? xtra : 0);
;             const char* a2 = last ? nA : cA + (size_t)(t + 2) * kstep + ((t + 2) >= 8 ? xtra : 0); const char* b2 = last ? nB : cB + (size_t)(t + 2) * kstep;
;             const char* a3 = a2 + kstep; const char* b3 = b2 + kstep;
;             PG8_LDB(B0, 0, 0); PG8_LDB(B1, 0, 1); PG8_SCHED; PG8_LDA(At, 0, 0); PG8_STAGE(PG8_SA(1, 1), a1 + hstepA, voffA);
;             PG8_WAIT_V(8); PG8_WAIT_L(0); PG8_BAR; PG8_MMA(0, 0, At, B0); PG8_MMA(0, 1, At, B1); PG8_BAR; PG8_SCHED;
;             PG8_LDA(At, 0, 1); PG8_STAGE(PG8_SB(0, 0), b2, voffB); PG8_STAGE(PG8_SB(0, 1), b2 + hstepB, voffB); PG8_STAGE(PG8_SA(0, 0), a2, voffA);
;             PG8_WAIT_V(8); PG8_WAIT_L(0); PG8_BAR; PG8_MMA(1, 0, At, B0); PG8_MMA(1, 1, At, B1); PG8_BAR; PG8_SCHED;
.LBB0_160:
	s_add_u32 s42, s94, 0x100
	s_addc_u32 s43, s95, 0
	s_add_i32 s8, 0, 0x10000
	v_add_u32_e32 v142, s8, v245
	v_add_u32_e32 v158, s15, v245
	ds_read_b128 v[122:125], v142
	ds_read_b128 v[126:129], v142 offset:1024
	ds_read_b128 v[138:141], v142 offset:2048
	ds_read_b128 v[142:145], v142 offset:3072
	ds_read_b128 v[146:149], v158
	ds_read_b128 v[150:153], v158 offset:1024
	ds_read_b128 v[154:157], v158 offset:2048
	ds_read_b128 v[158:161], v158 offset:3072
	s_cmp_eq_u32 s89, 12
	s_cselect_b32 vcc_hi, s91, s43
	s_cselect_b32 vcc_lo, s90, s42
	s_cselect_b32 s93, s36, s46
	s_cselect_b32 s92, s37, s45
	v_lshl_add_u64 v[210:211], s[94:95], 0, v[206:207]
	s_add_i32 m0, s19, 0xc000
	ds_read_b128 v[162:165], v246
	ds_read_b128 v[166:169], v246 offset:1024
	ds_read_b128 v[170:173], v246 offset:2048
	ds_read_b128 v[174:177], v246 offset:3072
	ds_read_b128 v[178:181], v246 offset:4096
	ds_read_b128 v[182:185], v246 offset:5120
	ds_read_b128 v[186:189], v246 offset:6144
	ds_read_b128 v[190:193], v246 offset:7168
	global_load_lds_dwordx4 v[210:211], off
	v_lshl_add_u64 v[210:211], s[94:95], 0, v[208:209]
	s_add_i32 m0, s19, 0xe000
	s_nop 0
	global_load_lds_dwordx4 v[210:211], off
	s_waitcnt vmcnt(8)
	s_waitcnt lgkmcnt(0)
	s_barrier
	s_setprio 1
	v_mfma_f32_16x16x32_bf16 v[134:137], v[122:125], v[162:165], v[134:137]
	v_mfma_f32_16x16x32_bf16 v[130:133], v[138:141], v[162:165], v[130:133]
	v_mfma_f32_16x16x32_bf16 v[108:111], v[122:125], v[170:173], v[108:111]
	v_mfma_f32_16x16x32_bf16 v[104:107], v[138:141], v[170:173], v[104:107]
	v_mfma_f32_16x16x32_bf16 v[92:95], v[122:125], v[178:181], v[92:95]
	v_mfma_f32_16x16x32_bf16 v[88:91], v[138:141], v[178:181], v[88:91]
	v_mfma_f32_16x16x32_bf16 v[76:79], v[122:125], v[186:189], v[76:79]
	v_mfma_f32_16x16x32_bf16 v[72:75], v[138:141], v[186:189], v[72:75]
	v_mfma_f32_16x16x32_bf16 v[134:137], v[126:129], v[166:169], v[134:137]
	v_mfma_f32_16x16x32_bf16 v[130:133], v[142:145], v[166:169], v[130:133]
	v_mfma_f32_16x16x32_bf16 v[108:111], v[126:129], v[174:177], v[108:111]
	v_mfma_f32_16x16x32_bf16 v[104:107], v[142:145], v[174:177], v[104:107]
	v_mfma_f32_16x16x32_bf16 v[92:95], v[126:129], v[182:185], v[92:95]
	v_mfma_f32_16x16x32_bf16 v[88:91], v[142:145], v[182:185], v[88:91]
	v_mfma_f32_16x16x32_bf16 v[76:79], v[126:129], v[190:193], v[76:79]
	v_mfma_f32_16x16x32_bf16 v[72:75], v[142:145], v[190:193], v[72:75]
	v_mfma_f32_16x16x32_bf16 v[118:121], v[146:149], v[162:165], v[118:121]
	v_mfma_f32_16x16x32_bf16 v[114:117], v[154:157], v[162:165], v[114:117]
	v_mfma_f32_16x16x32_bf16 v[100:103], v[146:149], v[170:173], v[100:103]
	v_mfma_f32_16x16x32_bf16 v[96:99], v[154:157], v[170:173], v[96:99]
	v_mfma_f32_16x16x32_bf16 v[84:87], v[146:149], v[178:181], v[84:87]
	v_mfma_f32_16x16x32_bf16 v[80:83], v[154:157], v[178:181], v[80:83]
	v_mfma_f32_16x16x32_bf16 v[68:71], v[146:149], v[186:189], v[68:71]
	v_mfma_f32_16x16x32_bf16 v[64:67], v[154:157], v[186:189], v[64:67]
	v_mfma_f32_16x16x32_bf16 v[118:121], v[150:153], v[166:169], v[118:121]
	v_mfma_f32_16x16x32_bf16 v[114:117], v[158:161], v[166:169], v[114:117]
	v_mfma_f32_16x16x32_bf16 v[100:103], v[150:153], v[174:177], v[100:103]
	v_mfma_f32_16x16x32_bf16 v[96:99], v[158:161], v[174:177], v[96:99]
	v_mfma_f32_16x16x32_bf16 v[84:87], v[150:153], v[182:185], v[84:87]
	v_mfma_f32_16x16x32_bf16 v[80:83], v[158:161], v[182:185], v[80:83]
	v_mfma_f32_16x16x32_bf16 v[68:71], v[150:153], v[190:193], v[68:71]
	v_mfma_f32_16x16x32_bf16 v[64:67], v[158:161], v[190:193], v[64:67]
	s_setprio 0
	s_barrier
	s_add_i32 s8, s8, s11
	v_lshl_add_u64 v[210:211], s[92:93], 0, v[112:113]
	s_mov_b32 m0, s8
	ds_read_b128 v[162:165], v246 offset:16384
	ds_read_b128 v[166:169], v246 offset:17408
	ds_read_b128 v[170:173], v246 offset:18432
	ds_read_b128 v[174:177], v246 offset:19456
	ds_read_b128 v[178:181], v246 offset:20480
	ds_read_b128 v[182:185], v246 offset:21504
	ds_read_b128 v[186:189], v246 offset:22528
	ds_read_b128 v[190:193], v246 offset:23552
	global_load_lds_dwordx4 v112, s[92:93]
	s_add_i32 m0, s8, 0x2000
	s_add_u32 s8, s92, 0x40000
	v_lshl_add_u64 v[212:213], s[92:93], 0, v[200:201]
	s_addc_u32 s9, s93, 0
	s_add_i32 s13, s15, s11
	global_load_lds_dwordx4 v200, s[92:93]
	s_nop 0
	s_mov_b32 m0, s13
	s_nop 0
	global_load_lds_dwordx4 v112, s[8:9]
	s_nop 0
	s_add_i32 m0, s13, 0x2000
	s_nop 0
	global_load_lds_dwordx4 v200, s[8:9]
	s_nop 0
	s_mov_b32 m0, s19
	s_nop 0
	global_load_lds_dwordx4 v202, vcc
	s_mov_b32 m0, s28
	s_nop 0
	global_load_lds_dwordx4 v204, vcc
	s_waitcnt vmcnt(8)
	s_waitcnt lgkmcnt(0)
	s_barrier
; #define PG8_STAGE(bufoff, gbase, voff) do { _Pragma("unroll") for (int _i = 0; _i < 2; ++_i) \
;         __builtin_amdgcn_global_load_lds((const unsigned*)((const char*)(gbase) + (voff)[_i]), (LAS unsigned*)(lds + (bufoff) + ldsw + _i * 8192), 16, 0, 0); } while (0)
; #define PG8_LDA(dst, b, h) do { _Pragma("unroll") for (int m = 0; m < 4; ++m) _Pragma("unroll") for (int k = 0; k < 2; ++k) dst[m][k] = *(const LAS bf16x8*)(lds + PG8_SA(b, h) + aoff + m * 2048 + k * 1024); } while (0)
; #define PG8_LDB(dst, b, h) do { _Pragma("unroll") for (int n = 0; n < 2; ++n) _Pragma("unroll") for (int k = 0; k < 2; ++k) dst[n][k] = *(const LAS bf16x8*)(lds + PG8_SB(b, h) + boff + n * 2048 + k * 1024); } while (0)
; #define PG8_MMA(ai, bj, At, Bt) do { __builtin_amdgcn_s_setprio(1); _Pragma("unroll") for (int m = 0; m < 4; ++m) _Pragma("unroll") for (int n = 0; n < 2; ++n) _Pragma("unroll") for (int k = 0; k < 2; ++k) \
;         acc[ai][bj][m][n] = __builtin_amdgcn_mfma_f32_16x16x32_bf16(Bt[n][k], At[m][k], acc[ai][bj][m][n], 0, 0, 0); __builtin_amdgcn_s_setprio(0); } while (0)
; #define PG8_WAIT_V(n) asm volatile("s_waitcnt vmcnt(" #n ")" ::: "memory")
; #define PG8_WAIT_L(n) asm volatile("s_waitcnt lgkmcnt(" #n ")" ::: "memory")
; #define PG8_BAR __builtin_amdgcn_s_barrier()
; #define PG8_SCHED __builtin_amdgcn_sched_barrier(0)
; template <class Epi>
; __device__ __forceinline__ void gemm_phase(LAS unsigned char* lds, const Gemm g, const StaticOrder& S, const Epi& E, const int tid) {
;     ...
;             PG8_WAIT_V(8); PG8_WAIT_L(0); PG8_BAR; PG8_MMA(1, 0, At, B0); PG8_MMA(1, 1, At, B1); PG8_BAR; PG8_SCHED;
;             PG8_LDB(B0, 1, 0); PG8_LDB(B1, 1, 1); PG8_SCHED; PG8_LDA(At, 1, 0); PG8_STAGE(PG8_SA(0, 1), a2 + hstepA, voffA);
;             PG8_WAIT_V(8); PG8_WAIT_L(0); PG8_BAR; PG8_MMA(0, 0, At, B0); PG8_MMA(0, 1, At, B1); PG8_BAR; PG8_SCHED;
	s_setprio 1
	v_mfma_f32_16x16x32_bf16 v[60:63], v[122:125], v[162:165], v[60:63]
	v_mfma_f32_16x16x32_bf16 v[56:59], v[138:141], v[162:165], v[56:59]
	v_mfma_f32_16x16x32_bf16 v[44:47], v[122:125], v[170:173], v[44:47]
	v_mfma_f32_16x16x32_bf16 v[40:43], v[138:141], v[170:173], v[40:43]
	v_mfma_f32_16x16x32_bf16 v[28:31], v[122:125], v[178:181], v[28:31]
	v_mfma_f32_16x16x32_bf16 v[24:27], v[138:141], v[178:181], v[24:27]
	v_mfma_f32_16x16x32_bf16 v[12:15], v[122:125], v[186:189], v[12:15]
	v_mfma_f32_16x16x32_bf16 v[8:11], v[138:141], v[186:189], v[8:11]
	v_mfma_f32_16x16x32_bf16 v[60:63], v[126:129], v[166:169], v[60:63]
	v_mfma_f32_16x16x32_bf16 v[56:59], v[142:145], v[166:169], v[56:59]
	v_mfma_f32_16x16x32_bf16 v[44:47], v[126:129], v[174:177], v[44:47]
	v_mfma_f32_16x16x32_bf16 v[40:43], v[142:145], v[174:177], v[40:43]
	v_mfma_f32_16x16x32_bf16 v[28:31], v[126:129], v[182:185], v[28:31]
	v_mfma_f32_16x16x32_bf16 v[24:27], v[142:145], v[182:185], v[24:27]
	v_mfma_f32_16x16x32_bf16 v[12:15], v[126:129], v[190:193], v[12:15]
	v_mfma_f32_16x16x32_bf16 v[8:11], v[142:145], v[190:193], v[8:11]
	v_mfma_f32_16x16x32_bf16 v[52:55], v[146:149], v[162:165], v[52:55]
	v_mfma_f32_16x16x32_bf16 v[48:51], v[154:157], v[162:165], v[48:51]
	v_mfma_f32_16x16x32_bf16 v[36:39], v[146:149], v[170:173], v[36:39]
	v_mfma_f32_16x16x32_bf16 v[32:35], v[154:157], v[170:173], v[32:35]
	v_mfma_f32_16x16x32_bf16 v[20:23], v[146:149], v[178:181], v[20:23]
	v_mfma_f32_16x16x32_bf16 v[16:19], v[154:157], v[178:181], v[16:19]
	v_mfma_f32_16x16x32_bf16 v[4:7], v[146:149], v[186:189], v[4:7]
	v_mfma_f32_16x16x32_bf16 v[0:3], v[154:157], v[186:189], v[0:3]
	v_mfma_f32_16x16x32_bf16 v[52:55], v[150:153], v[166:169], v[52:55]
	v_mfma_f32_16x16x32_bf16 v[48:51], v[158:161], v[166:169], v[48:51]
	v_mfma_f32_16x16x32_bf16 v[36:39], v[150:153], v[174:177], v[36:39]
	v_mfma_f32_16x16x32_bf16 v[32:35], v[158:161], v[174:177], v[32:35]
	v_mfma_f32_16x16x32_bf16 v[20:23], v[150:153], v[182:185], v[20:23]
	v_mfma_f32_16x16x32_bf16 v[16:19], v[158:161], v[182:185], v[16:19]
	v_mfma_f32_16x16x32_bf16 v[4:7], v[150:153], v[190:193], v[4:7]
	v_mfma_f32_16x16x32_bf16 v[0:3], v[158:161], v[190:193], v[0:3]
	s_setprio 0
	s_barrier
	s_add_i32 s13, 0, 0x18000
	s_add_i32 s31, 0, 0x1c000
	v_add_u32_e32 v142, s13, v245
	v_add_u32_e32 v158, s31, v245
	ds_read_b128 v[122:125], v142
	ds_read_b128 v[126:129], v142 offset:1024
	ds_read_b128 v[138:141], v142 offset:2048
	ds_read_b128 v[142:145], v142 offset:3072
	ds_read_b128 v[146:149], v158
	ds_read_b128 v[150:153], v158 offset:1024
	ds_read_b128 v[154:157], v158 offset:2048
	ds_read_b128 v[158:161], v158 offset:3072
	s_add_u32 s8, vcc_lo, 0xc0000
	s_addc_u32 s9, vcc_hi, 0
	s_mov_b32 m0, s30
	s_nop 0
	ds_read_b128 v[162:165], v246 offset:32768
	ds_read_b128 v[166:169], v246 offset:33792
	ds_read_b128 v[170:173], v246 offset:34816
	ds_read_b128 v[174:177], v246 offset:35840
	ds_read_b128 v[178:181], v246 offset:36864
	ds_read_b128 v[182:185], v246 offset:37888
	ds_read_b128 v[186:189], v246 offset:38912
	ds_read_b128 v[190:193], v246 offset:39936
	global_load_lds_dwordx4 v202, s[8:9]
	v_lshl_add_u64 v[248:249], s[8:9], 0, v[204:205]
	s_mov_b32 m0, s35
	s_nop 0
	global_load_lds_dwordx4 v204, s[8:9]
	s_waitcnt vmcnt(8)
	s_waitcnt lgkmcnt(0)
	s_barrier
	s_setprio 1
	v_mfma_f32_16x16x32_bf16 v[134:137], v[122:125], v[162:165], v[134:137]
	v_mfma_f32_16x16x32_bf16 v[130:133], v[138:141], v[162:165], v[130:133]
	v_mfma_f32_16x16x32_bf16 v[108:111], v[122:125], v[170:173], v[108:111]
	v_mfma_f32_16x16x32_bf16 v[104:107], v[138:141], v[170:173], v[104:107]
	v_mfma_f32_16x16x32_bf16 v[92:95], v[122:125], v[178:181], v[92:95]
	v_mfma_f32_16x16x32_bf16 v[88:91], v[138:141], v[178:181], v[88:91]
	v_mfma_f32_16x16x32_bf16 v[76:79], v[122:125], v[186:189], v[76:79]
	v_mfma_f32_16x16x32_bf16 v[72:75], v[138:141], v[186:189], v[72:75]
	v_mfma_f32_16x16x32_bf16 v[134:137], v[126:129], v[166:169], v[134:137]
	v_mfma_f32_16x16x32_bf16 v[130:133], v[142:145], v[166:169], v[130:133]
	v_mfma_f32_16x16x32_bf16 v[108:111], v[126:129], v[174:177], v[108:111]
	v_mfma_f32_16x16x32_bf16 v[104:107], v[142:145], v[174:177], v[104:107]
	v_mfma_f32_16x16x32_bf16 v[92:95], v[126:129], v[182:185], v[92:95]
	v_mfma_f32_16x16x32_bf16 v[88:91], v[142:145], v[182:185], v[88:91]
	v_mfma_f32_16x16x32_bf16 v[76:79], v[126:129], v[190:193], v[76:79]
	v_mfma_f32_16x16x32_bf16 v[72:75], v[142:145], v[190:193], v[72:75]
	v_mfma_f32_16x16x32_bf16 v[118:121], v[146:149], v[162:165], v[118:121]
	v_mfma_f32_16x16x32_bf16 v[114:117], v[154:157], v[162:165], v[114:117]
	v_mfma_f32_16x16x32_bf16 v[100:103], v[146:149], v[170:173], v[100:103]
	v_mfma_f32_16x16x32_bf16 v[96:99], v[154:157], v[170:173], v[96:99]
	v_mfma_f32_16x16x32_bf16 v[84:87], v[146:149], v[178:181], v[84:87]
	v_mfma_f32_16x16x32_bf16 v[80:83], v[154:157], v[178:181], v[80:83]
	v_mfma_f32_16x16x32_bf16 v[68:71], v[146:149], v[186:189], v[68:71]
	v_mfma_f32_16x16x32_bf16 v[64:67], v[154:157], v[186:189], v[64:67]
	v_mfma_f32_16x16x32_bf16 v[118:121], v[150:153], v[166:169], v[118:121]
	v_mfma_f32_16x16x32_bf16 v[114:117], v[158:161], v[166:169], v[114:117]
	v_mfma_f32_16x16x32_bf16 v[100:103], v[150:153], v[174:177], v[100:103]
	v_mfma_f32_16x16x32_bf16 v[96:99], v[158:161], v[174:177], v[96:99]
	v_mfma_f32_16x16x32_bf16 v[84:87], v[150:153], v[182:185], v[84:87]
	v_mfma_f32_16x16x32_bf16 v[80:83], v[158:161], v[182:185], v[80:83]
	v_mfma_f32_16x16x32_bf16 v[68:71], v[150:153], v[190:193], v[68:71]
	v_mfma_f32_16x16x32_bf16 v[64:67], v[158:161], v[190:193], v[64:67]
	s_setprio 0
	s_barrier
; #define PG8_STAGE(bufoff, gbase, voff) do { _Pragma("unroll") for (int _i = 0; _i < 2; ++_i) \
;         __builtin_amdgcn_global_load_lds((const unsigned*)((const char*)(gbase) + (voff)[_i]), (LAS unsigned*)(lds + (bufoff) + ldsw + _i * 8192), 16, 0, 0); } while (0)
; #define PG8_LDA(dst, b, h) do { _Pragma("unroll") for (int m = 0; m < 4; ++m) _Pragma("unroll") for (int k = 0; k < 2; ++k) dst[m][k] = *(const LAS bf16x8*)(lds + PG8_SA(b, h) + aoff + m * 2048 + k * 1024); } while (0)
; #define PG8_MMA(ai, bj, At, Bt) do { __builtin_amdgcn_s_setprio(1); _Pragma("unroll") for (int m = 0; m < 4; ++m) _Pragma("unroll") for (int n = 0; n < 2; ++n) _Pragma("unroll") for (int k = 0; k < 2; ++k) \
;         acc[ai][bj][m][n] = __builtin_amdgcn_mfma_f32_16x16x32_bf16(Bt[n][k], At[m][k], acc[ai][bj][m][n], 0, 0, 0); __builtin_amdgcn_s_setprio(0); } while (0)
; #define PG8_WAIT_V(n) asm volatile("s_waitcnt vmcnt(" #n ")" ::: "memory")
; #define PG8_WAIT_L(n) asm volatile("s_waitcnt lgkmcnt(" #n ")" ::: "memory")
; #define PG8_BAR __builtin_amdgcn_s_barrier()
; #define PG8_SCHED __builtin_amdgcn_sched_barrier(0)
; template <class Epi>
; __device__ __forceinline__ void gemm_phase(LAS unsigned char* lds, const Gemm g, const StaticOrder& S, const Epi& E, const int tid) {
;     ...
;             PG8_LDA(At, 1, 1); PG8_STAGE(PG8_SB(1, 0), b3, voffB); PG8_STAGE(PG8_SB(1, 1), b3 + hstepB, voffB); PG8_STAGE(PG8_SA(1, 0), a3, voffA);
;             PG8_WAIT_V(8); PG8_WAIT_L(0); PG8_BAR; PG8_MMA(1, 0, At, B0); PG8_MMA(1, 1, At, B1); PG8_BAR; PG8_SCHED;
;         }
;         if (wr == 0) PG8_BAR;
	s_add_i32 s8, s13, s11
	s_add_u32 s100, s92, 0x80
	s_addc_u32 s101, s93, 0
	s_mov_b32 m0, s8
	ds_read_b128 v[162:165], v246 offset:49152
	ds_read_b128 v[166:169], v246 offset:50176
	ds_read_b128 v[170:173], v246 offset:51200
	ds_read_b128 v[174:177], v246 offset:52224
	ds_read_b128 v[178:181], v246 offset:53248
	ds_read_b128 v[182:185], v246 offset:54272
	ds_read_b128 v[186:189], v246 offset:55296
	ds_read_b128 v[190:193], v246 offset:56320
	global_load_lds_dwordx4 v112, s[100:101]
	s_add_i32 m0, s8, 0x2000
	s_add_u32 s8, s92, 0x40080
	v_lshl_add_u64 v[210:211], v[212:213], 0, s[24:25]
	s_addc_u32 s9, s93, 0
	s_add_i32 s13, s31, s11
	global_load_lds_dwordx4 v[210:211], off
	s_nop 0
	s_mov_b32 m0, s13
	s_nop 0
	global_load_lds_dwordx4 v112, s[8:9]
	s_nop 0
	s_add_i32 m0, s13, 0x2000
	s_nop 0
	global_load_lds_dwordx4 v200, s[8:9]
	s_add_u32 s100, vcc_lo, 0x80
	s_addc_u32 s101, vcc_hi, 0
	s_mov_b32 m0, s38
	s_nop 0
	global_load_lds_dwordx4 v202, s[100:101]
	s_add_u32 s100, vcc_lo, 0x80
	s_addc_u32 s101, vcc_hi, 0
	s_mov_b32 m0, s39
	s_nop 0
	global_load_lds_dwordx4 v204, s[100:101]
	s_waitcnt vmcnt(8)
	s_waitcnt lgkmcnt(0)
	s_barrier
	s_setprio 1
	v_mfma_f32_16x16x32_bf16 v[60:63], v[122:125], v[162:165], v[60:63]
	v_mfma_f32_16x16x32_bf16 v[56:59], v[138:141], v[162:165], v[56:59]
	v_mfma_f32_16x16x32_bf16 v[44:47], v[122:125], v[170:173], v[44:47]
	v_mfma_f32_16x16x32_bf16 v[40:43], v[138:141], v[170:173], v[40:43]
	v_mfma_f32_16x16x32_bf16 v[28:31], v[122:125], v[178:181], v[28:31]
	v_mfma_f32_16x16x32_bf16 v[24:27], v[138:141], v[178:181], v[24:27]
	v_mfma_f32_16x16x32_bf16 v[12:15], v[122:125], v[186:189], v[12:15]
	v_mfma_f32_16x16x32_bf16 v[8:11], v[138:141], v[186:189], v[8:11]
	v_mfma_f32_16x16x32_bf16 v[60:63], v[126:129], v[166:169], v[60:63]
	v_mfma_f32_16x16x32_bf16 v[56:59], v[142:145], v[166:169], v[56:59]
	v_mfma_f32_16x16x32_bf16 v[44:47], v[126:129], v[174:177], v[44:47]
	v_mfma_f32_16x16x32_bf16 v[40:43], v[142:145], v[174:177], v[40:43]
	v_mfma_f32_16x16x32_bf16 v[28:31], v[126:129], v[182:185], v[28:31]
	v_mfma_f32_16x16x32_bf16 v[24:27], v[142:145], v[182:185], v[24:27]
	v_mfma_f32_16x16x32_bf16 v[12:15], v[126:129], v[190:193], v[12:15]
	v_mfma_f32_16x16x32_bf16 v[8:11], v[142:145], v[190:193], v[8:11]
	v_mfma_f32_16x16x32_bf16 v[52:55], v[146:149], v[162:165], v[52:55]
	v_mfma_f32_16x16x32_bf16 v[48:51], v[154:157], v[162:165], v[48:51]
	v_mfma_f32_16x16x32_bf16 v[36:39], v[146:149], v[170:173], v[36:39]
	v_mfma_f32_16x16x32_bf16 v[32:35], v[154:157], v[170:173], v[32:35]
	v_mfma_f32_16x16x32_bf16 v[20:23], v[146:149], v[178:181], v[20:23]
	v_mfma_f32_16x16x32_bf16 v[16:19], v[154:157], v[178:181], v[16:19]
	v_mfma_f32_16x16x32_bf16 v[4:7], v[146:149], v[186:189], v[4:7]
	v_mfma_f32_16x16x32_bf16 v[0:3], v[154:157], v[186:189], v[0:3]
	v_mfma_f32_16x16x32_bf16 v[52:55], v[150:153], v[166:169], v[52:55]
	v_mfma_f32_16x16x32_bf16 v[48:51], v[158:161], v[166:169], v[48:51]
	v_mfma_f32_16x16x32_bf16 v[36:39], v[150:153], v[174:177], v[36:39]
	v_mfma_f32_16x16x32_bf16 v[32:35], v[158:161], v[174:177], v[32:35]
	v_mfma_f32_16x16x32_bf16 v[20:23], v[150:153], v[182:185], v[20:23]
	v_mfma_f32_16x16x32_bf16 v[16:19], v[158:161], v[182:185], v[16:19]
	v_mfma_f32_16x16x32_bf16 v[4:7], v[150:153], v[190:193], v[4:7]
	v_mfma_f32_16x16x32_bf16 v[0:3], v[158:161], v[190:193], v[0:3]
	s_setprio 0
	s_barrier
	s_add_i32 s89, s89, 2
	s_add_u32 s45, s45, 0x100
	s_addc_u32 s46, s46, 0
	s_cmp_gt_u32 s89, 13
	s_mov_b64 s[94:95], s[42:43]
	s_cbranch_scc0 .LBB0_160
	s_and_b64 vcc, exec, s[86:87]
	s_cbranch_vccz .LBB0_163
	s_barrier

; #define PG8_STAGE(bufoff, gbase, voff) do { _Pragma("unroll") for (int _i = 0; _i < 2; ++_i) \
;         __builtin_amdgcn_global_load_lds((const unsigned*)((const char*)(gbase) + (voff)[_i]), (LAS unsigned*)(lds + (bufoff) + ldsw + _i * 8192), 16, 0, 0); } while (0)
; #define PG8_LDA(dst, b, h) do { _Pragma("unroll") for (int m = 0; m < 4; ++m) _Pragma("unroll") for (int k = 0; k < 2; ++k) dst[m][k] = *(const LAS bf16x8*)(lds + PG8_SA(b, h) + aoff + m * 2048 + k * 1024); } while (0)
; #define PG8_LDB(dst, b, h) do { _Pragma("unroll") for (int n = 0; n < 2; ++n) _Pragma("unroll") for (int k = 0; k < 2; ++k) dst[n][k] = *(const LAS bf16x8*)(lds + PG8_SB(b, h) + boff + n * 2048 + k * 1024); } while (0)
; #define PG8_MMA(ai, bj, At, Bt) do { __builtin_amdgcn_s_setprio(1); _Pragma("unroll") for (int m = 0; m < 4; ++m) _Pragma("unroll") for (int n = 0; n < 2; ++n) _Pragma("unroll") for (int k = 0; k < 2; ++k) \
;         acc[ai][bj][m][n] = __builtin_amdgcn_mfma_f32_16x16x32_bf16(Bt[n][k], At[m][k], acc[ai][bj][m][n], 0, 0, 0); __builtin_amdgcn_s_setprio(0); } while (0)
; #define PG8_WAIT_V(n) asm volatile("s_waitcnt vmcnt(" #n ")" ::: "memory")
; #define PG8_WAIT_L(n) asm volatile("s_waitcnt lgkmcnt(" #n ")" ::: "memory")
; #define PG8_BAR __builtin_amdgcn_s_barrier()
; template <class Epi>
; __device__ __forceinline__ void gemm_phase(LAS unsigned char* lds, const Gemm g, const StaticOrder& S, const Epi& E, const int tid) {
;     ...
;         for (int t = 0; t < nt; t += 2) {
;             const bool last = (t == nt - 2);
;             const char* a1 = cA + (size_t)(t + 1) * kstep + ((t + 1) >= 8 ? xtra : 0);
;             const char* a2 = last ? nA : cA + (size_t)(t + 2) * kstep + ((t + 2) >= 8 ? xtra : 0); const char* b2 = last ? nB : cB + (size_t)(t + 2) * kstep;
;             const char* a3 = a2 + kstep; const char* b3 = b2 + kstep;
;             PG8_LDB(B0, 0, 0); PG8_LDB(B1, 0, 1); PG8_SCHED; PG8_LDA(At, 0, 0); PG8_STAGE(PG8_SA(1, 1), a1 + hstepA, voffA);
;             PG8_WAIT_V(8); PG8_WAIT_L(0); PG8_BAR; PG8_MMA(0, 0, At, B0); PG8_MMA(0, 1, At, B1); PG8_BAR; PG8_SCHED;
;             PG8_LDA(At, 0, 1); PG8_STAGE(PG8_SB(0, 0), b2, voffB); PG8_STAGE(PG8_SB(0, 1), b2 + hstepB, voffB); PG8_STAGE(PG8_SA(0, 0), a2, voffA);
;             PG8_WAIT_V(8); PG8_WAIT_L(0); PG8_BAR; PG8_MMA(1, 0, At, B0); PG8_MMA(1, 1, At, B1); PG8_BAR; PG8_SCHED;
.LBB0_230:
	s_add_i32 s96, s40, 2
	s_cmp_gt_u32 s96, 7
	s_cselect_b32 s46, 0x600, 0
	s_cmp_gt_u32 s96, 5
	s_cselect_b32 s8, 0x600, 0
	s_add_u32 s8, s88, s8
	s_addc_u32 s9, s89, 0
	s_add_u32 s8, s8, 0x100
	s_addc_u32 s9, s9, 0
	s_add_i32 s13, 0, 0x10000
	v_add_u32_e32 v142, s13, v210
	v_add_u32_e32 v158, s15, v210
	ds_read_b128 v[130:133], v142
	ds_read_b128 v[134:137], v142 offset:1024
	ds_read_b128 v[138:141], v142 offset:2048
	ds_read_b128 v[142:145], v142 offset:3072
	ds_read_b128 v[146:149], v158
	ds_read_b128 v[150:153], v158 offset:1024
	ds_read_b128 v[154:157], v158 offset:2048
	ds_read_b128 v[158:161], v158 offset:3072
	s_cmp_eq_u32 s40, 12
	s_cselect_b32 s40, s87, vcc_lo
	s_cselect_b32 s91, s83, s9
	s_cselect_b32 s90, s82, s8
	s_cselect_b32 s41, s81, vcc_hi
	v_lshl_add_u64 v[212:213], s[88:89], 0, v[190:191]
	v_lshl_add_u64 v[212:213], v[212:213], 0, s[46:47]
	s_add_i32 m0, s19, 0xc000
	ds_read_b128 v[162:165], v211
	ds_read_b128 v[166:169], v211 offset:1024
	ds_read_b128 v[170:173], v211 offset:2048
	ds_read_b128 v[174:177], v211 offset:3072
	ds_read_b128 v[178:181], v211 offset:4096
	ds_read_b128 v[182:185], v211 offset:5120
	ds_read_b128 v[202:205], v211 offset:6144
	ds_read_b128 v[206:209], v211 offset:7168
	global_load_lds_dwordx4 v[212:213], off
	v_lshl_add_u64 v[212:213], s[88:89], 0, v[192:193]
	v_lshl_add_u64 v[212:213], v[212:213], 0, s[46:47]
	s_add_i32 m0, s19, 0xe000
	s_nop 0
	global_load_lds_dwordx4 v[212:213], off
	s_waitcnt vmcnt(8)
	s_waitcnt lgkmcnt(0)
	s_barrier
	s_setprio 1
	v_mfma_f32_16x16x32_bf16 v[126:129], v[130:133], v[162:165], v[126:129]
	v_mfma_f32_16x16x32_bf16 v[122:125], v[138:141], v[162:165], v[122:125]
	v_mfma_f32_16x16x32_bf16 v[108:111], v[130:133], v[170:173], v[108:111]
	v_mfma_f32_16x16x32_bf16 v[104:107], v[138:141], v[170:173], v[104:107]
	v_mfma_f32_16x16x32_bf16 v[92:95], v[130:133], v[178:181], v[92:95]
	v_mfma_f32_16x16x32_bf16 v[88:91], v[138:141], v[178:181], v[88:91]
	v_mfma_f32_16x16x32_bf16 v[76:79], v[130:133], v[202:205], v[76:79]
	v_mfma_f32_16x16x32_bf16 v[72:75], v[138:141], v[202:205], v[72:75]
	v_mfma_f32_16x16x32_bf16 v[126:129], v[134:137], v[166:169], v[126:129]
	v_mfma_f32_16x16x32_bf16 v[122:125], v[142:145], v[166:169], v[122:125]
	v_mfma_f32_16x16x32_bf16 v[108:111], v[134:137], v[174:177], v[108:111]
	v_mfma_f32_16x16x32_bf16 v[104:107], v[142:145], v[174:177], v[104:107]
	v_mfma_f32_16x16x32_bf16 v[92:95], v[134:137], v[182:185], v[92:95]
	v_mfma_f32_16x16x32_bf16 v[88:91], v[142:145], v[182:185], v[88:91]
	v_mfma_f32_16x16x32_bf16 v[76:79], v[134:137], v[206:209], v[76:79]
	v_mfma_f32_16x16x32_bf16 v[72:75], v[142:145], v[206:209], v[72:75]
	v_mfma_f32_16x16x32_bf16 v[118:121], v[146:149], v[162:165], v[118:121]
	v_mfma_f32_16x16x32_bf16 v[114:117], v[154:157], v[162:165], v[114:117]
	v_mfma_f32_16x16x32_bf16 v[100:103], v[146:149], v[170:173], v[100:103]
	v_mfma_f32_16x16x32_bf16 v[96:99], v[154:157], v[170:173], v[96:99]
	v_mfma_f32_16x16x32_bf16 v[84:87], v[146:149], v[178:181], v[84:87]
	v_mfma_f32_16x16x32_bf16 v[80:83], v[154:157], v[178:181], v[80:83]
	v_mfma_f32_16x16x32_bf16 v[68:71], v[146:149], v[202:205], v[68:71]
	v_mfma_f32_16x16x32_bf16 v[64:67], v[154:157], v[202:205], v[64:67]
	v_mfma_f32_16x16x32_bf16 v[118:121], v[150:153], v[166:169], v[118:121]
	v_mfma_f32_16x16x32_bf16 v[114:117], v[158:161], v[166:169], v[114:117]
	v_mfma_f32_16x16x32_bf16 v[100:103], v[150:153], v[174:177], v[100:103]
	v_mfma_f32_16x16x32_bf16 v[96:99], v[158:161], v[174:177], v[96:99]
	v_mfma_f32_16x16x32_bf16 v[84:87], v[150:153], v[182:185], v[84:87]
	v_mfma_f32_16x16x32_bf16 v[80:83], v[158:161], v[182:185], v[80:83]
	v_mfma_f32_16x16x32_bf16 v[68:71], v[150:153], v[206:209], v[68:71]
	v_mfma_f32_16x16x32_bf16 v[64:67], v[158:161], v[206:209], v[64:67]
	s_setprio 0
	s_barrier
	s_add_i32 s8, s13, s11
	v_lshl_add_u64 v[212:213], s[40:41], 0, v[112:113]
	s_mov_b32 m0, s8
	ds_read_b128 v[162:165], v211 offset:16384
	ds_read_b128 v[166:169], v211 offset:17408
	ds_read_b128 v[170:173], v211 offset:18432
	ds_read_b128 v[174:177], v211 offset:19456
	ds_read_b128 v[178:181], v211 offset:20480
	ds_read_b128 v[182:185], v211 offset:21504
	ds_read_b128 v[202:205], v211 offset:22528
	ds_read_b128 v[206:209], v211 offset:23552
	global_load_lds_dwordx4 v112, s[40:41]
	s_add_i32 m0, s8, 0x2000
	s_add_u32 s8, s40, 0x40000
	v_lshl_add_u64 v[214:215], s[40:41], 0, v[200:201]
	s_addc_u32 s9, s41, 0
	s_add_i32 s13, s15, s11
	global_load_lds_dwordx4 v200, s[40:41]
	s_nop 0
	s_mov_b32 m0, s13
	v_lshl_add_u64 v[236:237], s[90:91], 0, v[188:189]
	global_load_lds_dwordx4 v112, s[8:9]
	s_nop 0
	s_add_i32 m0, s13, 0x2000
	s_nop 0
	global_load_lds_dwordx4 v200, s[8:9]
	s_nop 0
	s_mov_b32 m0, s19
	s_nop 0
	global_load_lds_dwordx4 v186, s[90:91]
	s_mov_b32 m0, s23
	s_nop 0
	global_load_lds_dwordx4 v188, s[90:91]
	s_waitcnt vmcnt(8)
	s_waitcnt lgkmcnt(0)
	s_barrier
; #define PG8_STAGE(bufoff, gbase, voff) do { _Pragma("unroll") for (int _i = 0; _i < 2; ++_i) \
;         __builtin_amdgcn_global_load_lds((const unsigned*)((const char*)(gbase) + (voff)[_i]), (LAS unsigned*)(lds + (bufoff) + ldsw + _i * 8192), 16, 0, 0); } while (0)
; #define PG8_LDA(dst, b, h) do { _Pragma("unroll") for (int m = 0; m < 4; ++m) _Pragma("unroll") for (int k = 0; k < 2; ++k) dst[m][k] = *(const LAS bf16x8*)(lds + PG8_SA(b, h) + aoff + m * 2048 + k * 1024); } while (0)
; #define PG8_LDB(dst, b, h) do { _Pragma("unroll") for (int n = 0; n < 2; ++n) _Pragma("unroll") for (int k = 0; k < 2; ++k) dst[n][k] = *(const LAS bf16x8*)(lds + PG8_SB(b, h) + boff + n * 2048 + k * 1024); } while (0)
; #define PG8_MMA(ai, bj, At, Bt) do { __builtin_amdgcn_s_setprio(1); _Pragma("unroll") for (int m = 0; m < 4; ++m) _Pragma("unroll") for (int n = 0; n < 2; ++n) _Pragma("unroll") for (int k = 0; k < 2; ++k) \
;         acc[ai][bj][m][n] = __builtin_amdgcn_mfma_f32_16x16x32_bf16(Bt[n][k], At[m][k], acc[ai][bj][m][n], 0, 0, 0); __builtin_amdgcn_s_setprio(0); } while (0)
; #define PG8_WAIT_V(n) asm volatile("s_waitcnt vmcnt(" #n ")" ::: "memory")
; #define PG8_WAIT_L(n) asm volatile("s_waitcnt lgkmcnt(" #n ")" ::: "memory")
; #define PG8_BAR __builtin_amdgcn_s_barrier()
; #define PG8_SCHED __builtin_amdgcn_sched_barrier(0)
; template <class Epi>
; __device__ __forceinline__ void gemm_phase(LAS unsigned char* lds, const Gemm g, const StaticOrder& S, const Epi& E, const int tid) {
;     ...
;             PG8_WAIT_V(8); PG8_WAIT_L(0); PG8_BAR; PG8_MMA(1, 0, At, B0); PG8_MMA(1, 1, At, B1); PG8_BAR; PG8_SCHED;
;             PG8_LDB(B0, 1, 0); PG8_LDB(B1, 1, 1); PG8_SCHED; PG8_LDA(At, 1, 0); PG8_STAGE(PG8_SA(0, 1), a2 + hstepA, voffA);
;             PG8_WAIT_V(8); PG8_WAIT_L(0); PG8_BAR; PG8_MMA(0, 0, At, B0); PG8_MMA(0, 1, At, B1); PG8_BAR; PG8_SCHED;
	s_setprio 1
	v_mfma_f32_16x16x32_bf16 v[60:63], v[130:133], v[162:165], v[60:63]
	v_mfma_f32_16x16x32_bf16 v[56:59], v[138:141], v[162:165], v[56:59]
	v_mfma_f32_16x16x32_bf16 v[44:47], v[130:133], v[170:173], v[44:47]
	v_mfma_f32_16x16x32_bf16 v[40:43], v[138:141], v[170:173], v[40:43]
	v_mfma_f32_16x16x32_bf16 v[28:31], v[130:133], v[178:181], v[28:31]
	v_mfma_f32_16x16x32_bf16 v[24:27], v[138:141], v[178:181], v[24:27]
	v_mfma_f32_16x16x32_bf16 v[12:15], v[130:133], v[202:205], v[12:15]
	v_mfma_f32_16x16x32_bf16 v[8:11], v[138:141], v[202:205], v[8:11]
	v_mfma_f32_16x16x32_bf16 v[60:63], v[134:137], v[166:169], v[60:63]
	v_mfma_f32_16x16x32_bf16 v[56:59], v[142:145], v[166:169], v[56:59]
	v_mfma_f32_16x16x32_bf16 v[44:47], v[134:137], v[174:177], v[44:47]
	v_mfma_f32_16x16x32_bf16 v[40:43], v[142:145], v[174:177], v[40:43]
	v_mfma_f32_16x16x32_bf16 v[28:31], v[134:137], v[182:185], v[28:31]
	v_mfma_f32_16x16x32_bf16 v[24:27], v[142:145], v[182:185], v[24:27]
	v_mfma_f32_16x16x32_bf16 v[12:15], v[134:137], v[206:209], v[12:15]
	v_mfma_f32_16x16x32_bf16 v[8:11], v[142:145], v[206:209], v[8:11]
	v_mfma_f32_16x16x32_bf16 v[52:55], v[146:149], v[162:165], v[52:55]
	v_mfma_f32_16x16x32_bf16 v[48:51], v[154:157], v[162:165], v[48:51]
	v_mfma_f32_16x16x32_bf16 v[36:39], v[146:149], v[170:173], v[36:39]
	v_mfma_f32_16x16x32_bf16 v[32:35], v[154:157], v[170:173], v[32:35]
	v_mfma_f32_16x16x32_bf16 v[20:23], v[146:149], v[178:181], v[20:23]
	v_mfma_f32_16x16x32_bf16 v[16:19], v[154:157], v[178:181], v[16:19]
	v_mfma_f32_16x16x32_bf16 v[4:7], v[146:149], v[202:205], v[4:7]
	v_mfma_f32_16x16x32_bf16 v[0:3], v[154:157], v[202:205], v[0:3]
	v_mfma_f32_16x16x32_bf16 v[52:55], v[150:153], v[166:169], v[52:55]
	v_mfma_f32_16x16x32_bf16 v[48:51], v[158:161], v[166:169], v[48:51]
	v_mfma_f32_16x16x32_bf16 v[36:39], v[150:153], v[174:177], v[36:39]
	v_mfma_f32_16x16x32_bf16 v[32:35], v[158:161], v[174:177], v[32:35]
	v_mfma_f32_16x16x32_bf16 v[20:23], v[150:153], v[182:185], v[20:23]
	v_mfma_f32_16x16x32_bf16 v[16:19], v[158:161], v[182:185], v[16:19]
	v_mfma_f32_16x16x32_bf16 v[4:7], v[150:153], v[206:209], v[4:7]
	v_mfma_f32_16x16x32_bf16 v[0:3], v[158:161], v[206:209], v[0:3]
	s_setprio 0
	s_barrier
	s_add_i32 s13, 0, 0x18000
	s_add_i32 s31, 0, 0x1c000
	v_add_u32_e32 v142, s13, v210
	v_add_u32_e32 v158, s31, v210
	ds_read_b128 v[130:133], v142
	ds_read_b128 v[134:137], v142 offset:1024
	ds_read_b128 v[138:141], v142 offset:2048
	ds_read_b128 v[142:145], v142 offset:3072
	ds_read_b128 v[146:149], v158
	ds_read_b128 v[150:153], v158 offset:1024
	ds_read_b128 v[154:157], v158 offset:2048
	ds_read_b128 v[158:161], v158 offset:3072
	s_add_u32 s8, s90, 0x90000
	s_addc_u32 s9, s91, 0
	s_mov_b32 m0, s28
	s_nop 0
	ds_read_b128 v[162:165], v211 offset:32768
	ds_read_b128 v[166:169], v211 offset:33792
	ds_read_b128 v[170:173], v211 offset:34816
	ds_read_b128 v[174:177], v211 offset:35840
	ds_read_b128 v[178:181], v211 offset:36864
	ds_read_b128 v[182:185], v211 offset:37888
	ds_read_b128 v[202:205], v211 offset:38912
	ds_read_b128 v[206:209], v211 offset:39936
	global_load_lds_dwordx4 v186, s[8:9]
	v_lshl_add_u64 v[238:239], s[8:9], 0, v[188:189]
	s_mov_b32 m0, s30
	s_nop 0
	global_load_lds_dwordx4 v188, s[8:9]
	s_waitcnt vmcnt(8)
	s_waitcnt lgkmcnt(0)
	s_barrier
	s_setprio 1
	v_mfma_f32_16x16x32_bf16 v[126:129], v[130:133], v[162:165], v[126:129]
	v_mfma_f32_16x16x32_bf16 v[122:125], v[138:141], v[162:165], v[122:125]
	v_mfma_f32_16x16x32_bf16 v[108:111], v[130:133], v[170:173], v[108:111]
	v_mfma_f32_16x16x32_bf16 v[104:107], v[138:141], v[170:173], v[104:107]
	v_mfma_f32_16x16x32_bf16 v[92:95], v[130:133], v[178:181], v[92:95]
	v_mfma_f32_16x16x32_bf16 v[88:91], v[138:141], v[178:181], v[88:91]
	v_mfma_f32_16x16x32_bf16 v[76:79], v[130:133], v[202:205], v[76:79]
	v_mfma_f32_16x16x32_bf16 v[72:75], v[138:141], v[202:205], v[72:75]
	v_mfma_f32_16x16x32_bf16 v[126:129], v[134:137], v[166:169], v[126:129]
	v_mfma_f32_16x16x32_bf16 v[122:125], v[142:145], v[166:169], v[122:125]
	v_mfma_f32_16x16x32_bf16 v[108:111], v[134:137], v[174:177], v[108:111]
	v_mfma_f32_16x16x32_bf16 v[104:107], v[142:145], v[174:177], v[104:107]
	v_mfma_f32_16x16x32_bf16 v[92:95], v[134:137], v[182:185], v[92:95]
	v_mfma_f32_16x16x32_bf16 v[88:91], v[142:145], v[182:185], v[88:91]
	v_mfma_f32_16x16x32_bf16 v[76:79], v[134:137], v[206:209], v[76:79]
	v_mfma_f32_16x16x32_bf16 v[72:75], v[142:145], v[206:209], v[72:75]
	v_mfma_f32_16x16x32_bf16 v[118:121], v[146:149], v[162:165], v[118:121]
	v_mfma_f32_16x16x32_bf16 v[114:117], v[154:157], v[162:165], v[114:117]
	v_mfma_f32_16x16x32_bf16 v[100:103], v[146:149], v[170:173], v[100:103]
	v_mfma_f32_16x16x32_bf16 v[96:99], v[154:157], v[170:173], v[96:99]
	v_mfma_f32_16x16x32_bf16 v[84:87], v[146:149], v[178:181], v[84:87]
	v_mfma_f32_16x16x32_bf16 v[80:83], v[154:157], v[178:181], v[80:83]
	v_mfma_f32_16x16x32_bf16 v[68:71], v[146:149], v[202:205], v[68:71]
	v_mfma_f32_16x16x32_bf16 v[64:67], v[154:157], v[202:205], v[64:67]
	v_mfma_f32_16x16x32_bf16 v[118:121], v[150:153], v[166:169], v[118:121]
	v_mfma_f32_16x16x32_bf16 v[114:117], v[158:161], v[166:169], v[114:117]
	v_mfma_f32_16x16x32_bf16 v[100:103], v[150:153], v[174:177], v[100:103]
	v_mfma_f32_16x16x32_bf16 v[96:99], v[158:161], v[174:177], v[96:99]
	v_mfma_f32_16x16x32_bf16 v[84:87], v[150:153], v[182:185], v[84:87]
	v_mfma_f32_16x16x32_bf16 v[80:83], v[158:161], v[182:185], v[80:83]
	v_mfma_f32_16x16x32_bf16 v[68:71], v[150:153], v[206:209], v[68:71]
	v_mfma_f32_16x16x32_bf16 v[64:67], v[158:161], v[206:209], v[64:67]
	s_setprio 0
	s_barrier
; #define PG8_STAGE(bufoff, gbase, voff) do { _Pragma("unroll") for (int _i = 0; _i < 2; ++_i) \
;         __builtin_amdgcn_global_load_lds((const unsigned*)((const char*)(gbase) + (voff)[_i]), (LAS unsigned*)(lds + (bufoff) + ldsw + _i * 8192), 16, 0, 0); } while (0)
; #define PG8_LDA(dst, b, h) do { _Pragma("unroll") for (int m = 0; m < 4; ++m) _Pragma("unroll") for (int k = 0; k < 2; ++k) dst[m][k] = *(const LAS bf16x8*)(lds + PG8_SA(b, h) + aoff + m * 2048 + k * 1024); } while (0)
; #define PG8_MMA(ai, bj, At, Bt) do { __builtin_amdgcn_s_setprio(1); _Pragma("unroll") for (int m = 0; m < 4; ++m) _Pragma("unroll") for (int n = 0; n < 2; ++n) _Pragma("unroll") for (int k = 0; k < 2; ++k) \
;         acc[ai][bj][m][n] = __builtin_amdgcn_mfma_f32_16x16x32_bf16(Bt[n][k], At[m][k], acc[ai][bj][m][n], 0, 0, 0); __builtin_amdgcn_s_setprio(0); } while (0)
; #define PG8_WAIT_V(n) asm volatile("s_waitcnt vmcnt(" #n ")" ::: "memory")
; #define PG8_WAIT_L(n) asm volatile("s_waitcnt lgkmcnt(" #n ")" ::: "memory")
; #define PG8_BAR __builtin_amdgcn_s_barrier()
; #define PG8_SCHED __builtin_amdgcn_sched_barrier(0)
; template <class Epi>
; __device__ __forceinline__ void gemm_phase(LAS unsigned char* lds, const Gemm g, const StaticOrder& S, const Epi& E, const int tid) {
;     ...
;             PG8_LDA(At, 1, 1); PG8_STAGE(PG8_SB(1, 0), b3, voffB); PG8_STAGE(PG8_SB(1, 1), b3 + hstepB, voffB); PG8_STAGE(PG8_SA(1, 0), a3, voffA);
;             PG8_WAIT_V(8); PG8_WAIT_L(0); PG8_BAR; PG8_MMA(1, 0, At, B0); PG8_MMA(1, 1, At, B1); PG8_BAR; PG8_SCHED;
;         }
;         if (wr == 0) PG8_BAR;
	s_add_i32 s8, s13, s11
	s_add_u32 s100, s40, 0x80
	s_addc_u32 s101, s41, 0
	s_mov_b32 m0, s8
	ds_read_b128 v[162:165], v211 offset:49152
	ds_read_b128 v[166:169], v211 offset:50176
	ds_read_b128 v[170:173], v211 offset:51200
	ds_read_b128 v[174:177], v211 offset:52224
	ds_read_b128 v[178:181], v211 offset:53248
	ds_read_b128 v[182:185], v211 offset:54272
	ds_read_b128 v[202:205], v211 offset:55296
	ds_read_b128 v[206:209], v211 offset:56320
	global_load_lds_dwordx4 v112, s[100:101]
	s_add_i32 m0, s8, 0x2000
	s_add_u32 s8, s40, 0x40080
	v_lshl_add_u64 v[212:213], v[214:215], 0, s[24:25]
	s_addc_u32 s9, s41, 0
	s_add_i32 s13, s31, s11
	global_load_lds_dwordx4 v[212:213], off
	s_nop 0
	s_mov_b32 m0, s13
	s_nop 0
	global_load_lds_dwordx4 v112, s[8:9]
	s_nop 0
	s_add_i32 m0, s13, 0x2000
	s_nop 0
	global_load_lds_dwordx4 v200, s[8:9]
	s_add_u32 s100, s90, 0x80
	s_addc_u32 s101, s91, 0
	s_mov_b32 m0, s99
	s_nop 0
	global_load_lds_dwordx4 v186, s[100:101]
	s_add_u32 s100, s90, 0x80
	s_addc_u32 s101, s91, 0
	s_mov_b32 m0, s33
	s_nop 0
	global_load_lds_dwordx4 v188, s[100:101]
	s_waitcnt vmcnt(8)
	s_waitcnt lgkmcnt(0)
	s_barrier
	s_setprio 1
	v_mfma_f32_16x16x32_bf16 v[60:63], v[130:133], v[162:165], v[60:63]
	v_mfma_f32_16x16x32_bf16 v[56:59], v[138:141], v[162:165], v[56:59]
	v_mfma_f32_16x16x32_bf16 v[44:47], v[130:133], v[170:173], v[44:47]
	v_mfma_f32_16x16x32_bf16 v[40:43], v[138:141], v[170:173], v[40:43]
	v_mfma_f32_16x16x32_bf16 v[28:31], v[130:133], v[178:181], v[28:31]
	v_mfma_f32_16x16x32_bf16 v[24:27], v[138:141], v[178:181], v[24:27]
	v_mfma_f32_16x16x32_bf16 v[12:15], v[130:133], v[202:205], v[12:15]
	v_mfma_f32_16x16x32_bf16 v[8:11], v[138:141], v[202:205], v[8:11]
	v_mfma_f32_16x16x32_bf16 v[60:63], v[134:137], v[166:169], v[60:63]
	v_mfma_f32_16x16x32_bf16 v[56:59], v[142:145], v[166:169], v[56:59]
	v_mfma_f32_16x16x32_bf16 v[44:47], v[134:137], v[174:177], v[44:47]
	v_mfma_f32_16x16x32_bf16 v[40:43], v[142:145], v[174:177], v[40:43]
	v_mfma_f32_16x16x32_bf16 v[28:31], v[134:137], v[182:185], v[28:31]
	v_mfma_f32_16x16x32_bf16 v[24:27], v[142:145], v[182:185], v[24:27]
	v_mfma_f32_16x16x32_bf16 v[12:15], v[134:137], v[206:209], v[12:15]
	v_mfma_f32_16x16x32_bf16 v[8:11], v[142:145], v[206:209], v[8:11]
	v_mfma_f32_16x16x32_bf16 v[52:55], v[146:149], v[162:165], v[52:55]
	v_mfma_f32_16x16x32_bf16 v[48:51], v[154:157], v[162:165], v[48:51]
	v_mfma_f32_16x16x32_bf16 v[36:39], v[146:149], v[170:173], v[36:39]
	v_mfma_f32_16x16x32_bf16 v[32:35], v[154:157], v[170:173], v[32:35]
	v_mfma_f32_16x16x32_bf16 v[20:23], v[146:149], v[178:181], v[20:23]
	v_mfma_f32_16x16x32_bf16 v[16:19], v[154:157], v[178:181], v[16:19]
	v_mfma_f32_16x16x32_bf16 v[4:7], v[146:149], v[202:205], v[4:7]
	v_mfma_f32_16x16x32_bf16 v[0:3], v[154:157], v[202:205], v[0:3]
	v_mfma_f32_16x16x32_bf16 v[52:55], v[150:153], v[166:169], v[52:55]
	v_mfma_f32_16x16x32_bf16 v[48:51], v[158:161], v[166:169], v[48:51]
	v_mfma_f32_16x16x32_bf16 v[36:39], v[150:153], v[174:177], v[36:39]
	v_mfma_f32_16x16x32_bf16 v[32:35], v[158:161], v[174:177], v[32:35]
	v_mfma_f32_16x16x32_bf16 v[20:23], v[150:153], v[182:185], v[20:23]
	v_mfma_f32_16x16x32_bf16 v[16:19], v[158:161], v[182:185], v[16:19]
	v_mfma_f32_16x16x32_bf16 v[4:7], v[150:153], v[206:209], v[4:7]
	v_mfma_f32_16x16x32_bf16 v[0:3], v[158:161], v[206:209], v[0:3]
	s_setprio 0
	s_barrier
	s_add_u32 s88, s88, 0x100
	s_addc_u32 s89, s89, 0
	s_add_u32 vcc_lo, vcc_lo, 0x100
	s_addc_u32 vcc_hi, vcc_hi, 0
	s_cmp_gt_u32 s96, 13
	s_mov_b32 s40, s96
	s_cbranch_scc0 .LBB0_230
	s_and_b64 vcc, exec, s[44:45]
	s_cbranch_vccz .LBB0_233
	s_barrier

; #define PG8_STAGE(bufoff, gbase, voff) do { _Pragma("unroll") for (int _i = 0; _i < 2; ++_i) \
;         __builtin_amdgcn_global_load_lds((const unsigned*)((const char*)(gbase) + (voff)[_i]), (LAS unsigned*)(lds + (bufoff) + ldsw + _i * 8192), 16, 0, 0); } while (0)
; #define PG8_LDA(dst, b, h) do { _Pragma("unroll") for (int m = 0; m < 4; ++m) _Pragma("unroll") for (int k = 0; k < 2; ++k) dst[m][k] = *(const LAS bf16x8*)(lds + PG8_SA(b, h) + aoff + m * 2048 + k * 1024); } while (0)
; #define PG8_LDB(dst, b, h) do { _Pragma("unroll") for (int n = 0; n < 2; ++n) _Pragma("unroll") for (int k = 0; k < 2; ++k) dst[n][k] = *(const LAS bf16x8*)(lds + PG8_SB(b, h) + boff + n * 2048 + k * 1024); } while (0)
; #define PG8_MMA(ai, bj, At, Bt) do { __builtin_amdgcn_s_setprio(1); _Pragma("unroll") for (int m = 0; m < 4; ++m) _Pragma("unroll") for (int n = 0; n < 2; ++n) _Pragma("unroll") for (int k = 0; k < 2; ++k) \
;         acc[ai][bj][m][n] = __builtin_amdgcn_mfma_f32_16x16x32_bf16(Bt[n][k], At[m][k], acc[ai][bj][m][n], 0, 0, 0); __builtin_amdgcn_s_setprio(0); } while (0)
; #define PG8_WAIT_V(n) asm volatile("s_waitcnt vmcnt(" #n ")" ::: "memory")
; #define PG8_WAIT_L(n) asm volatile("s_waitcnt lgkmcnt(" #n ")" ::: "memory")
; #define PG8_BAR __builtin_amdgcn_s_barrier()
; template <class Epi>
; __device__ __forceinline__ void gemm_phase(LAS unsigned char* lds, const Gemm g, const StaticOrder& S, const Epi& E, const int tid) {
;     ...
;         for (int t = 0; t < nt; t += 2) {
;             const bool last = (t == nt - 2);
;             const char* a1 = cA + (size_t)(t + 1) * kstep + ((t + 1) >= 8 ? xtra : 0);
;             const char* a2 = last ? nA : cA + (size_t)(t + 2) * kstep + ((t + 2) >= 8 ? xtra : 0); const char* b2 = last ? nB : cB + (size_t)(t + 2) * kstep;
;             const char* a3 = a2 + kstep; const char* b3 = b2 + kstep;
;             PG8_LDB(B0, 0, 0); PG8_LDB(B1, 0, 1); PG8_SCHED; PG8_LDA(At, 0, 0); PG8_STAGE(PG8_SA(1, 1), a1 + hstepA, voffA);
;             PG8_WAIT_V(8); PG8_WAIT_L(0); PG8_BAR; PG8_MMA(0, 0, At, B0); PG8_MMA(0, 1, At, B1); PG8_BAR; PG8_SCHED;
;             PG8_LDA(At, 0, 1); PG8_STAGE(PG8_SB(0, 0), b2, voffB); PG8_STAGE(PG8_SB(0, 1), b2 + hstepB, voffB); PG8_STAGE(PG8_SA(0, 0), a2, voffA);
;             PG8_WAIT_V(8); PG8_WAIT_L(0); PG8_BAR; PG8_MMA(1, 0, At, B0); PG8_MMA(1, 1, At, B1); PG8_BAR; PG8_SCHED;
.LBB0_268:
	s_add_u32 s8, s40, 0xfffc0080
	s_addc_u32 s9, s41, -1
	s_add_i32 s13, 0, 0x10000
	v_add_u32_e32 v162, s13, v167
	ds_read_b128 v[150:153], v162
	ds_read_b128 v[154:157], v162 offset:1024
	ds_read_b128 v[158:161], v162 offset:2048
	ds_read_b128 v[170:173], v162 offset:3072
	v_add_u32_e32 v162, s15, v167
	ds_read_b128 v[174:177], v162
	ds_read_b128 v[178:181], v162 offset:1024
	ds_read_b128 v[182:185], v162 offset:2048
	ds_read_b128 v[186:189], v162 offset:3072
	s_cmp_eq_u32 s85, 12
	s_cselect_b32 vcc_hi, s33, s9
	s_cselect_b32 vcc_lo, s36, s8
	s_cselect_b32 s95, s37, s57
	s_cselect_b32 s94, s45, s46
	s_nop 0
	s_add_i32 m0, s11, 0xc000
	ds_read_b128 v[190:193], v169
	ds_read_b128 v[200:203], v169 offset:1024
	ds_read_b128 v[204:207], v169 offset:2048
	ds_read_b128 v[208:211], v169 offset:3072
	ds_read_b128 v[212:215], v169 offset:4096
	ds_read_b128 v[234:237], v169 offset:5120
	ds_read_b128 v[238:241], v169 offset:6144
	ds_read_b128 v[242:245], v169 offset:7168
	global_load_lds_dwordx4 v146, s[40:41]
	s_nop 0
	s_add_i32 m0, s11, 0xe000
	s_nop 0
	global_load_lds_dwordx4 v148, s[40:41]
	s_waitcnt vmcnt(8)
	s_waitcnt lgkmcnt(0)
	s_barrier
	s_setprio 1
	v_mfma_f32_16x16x32_bf16 v[134:137], v[150:153], v[190:193], v[134:137]
	v_mfma_f32_16x16x32_bf16 v[130:133], v[158:161], v[190:193], v[130:133]
	v_mfma_f32_16x16x32_bf16 v[118:121], v[150:153], v[204:207], v[118:121]
	v_mfma_f32_16x16x32_bf16 v[114:117], v[158:161], v[204:207], v[114:117]
	v_mfma_f32_16x16x32_bf16 v[100:103], v[150:153], v[212:215], v[100:103]
	v_mfma_f32_16x16x32_bf16 v[96:99], v[158:161], v[212:215], v[96:99]
	v_mfma_f32_16x16x32_bf16 v[84:87], v[150:153], v[238:241], v[84:87]
	v_mfma_f32_16x16x32_bf16 v[80:83], v[158:161], v[238:241], v[80:83]
	v_mfma_f32_16x16x32_bf16 v[134:137], v[154:157], v[200:203], v[134:137]
	v_mfma_f32_16x16x32_bf16 v[130:133], v[170:173], v[200:203], v[130:133]
	v_mfma_f32_16x16x32_bf16 v[118:121], v[154:157], v[208:211], v[118:121]
	v_mfma_f32_16x16x32_bf16 v[114:117], v[170:173], v[208:211], v[114:117]
	v_mfma_f32_16x16x32_bf16 v[100:103], v[154:157], v[234:237], v[100:103]
	v_mfma_f32_16x16x32_bf16 v[96:99], v[170:173], v[234:237], v[96:99]
	v_mfma_f32_16x16x32_bf16 v[84:87], v[154:157], v[242:245], v[84:87]
	v_mfma_f32_16x16x32_bf16 v[80:83], v[170:173], v[242:245], v[80:83]
	v_mfma_f32_16x16x32_bf16 v[126:129], v[174:177], v[190:193], v[126:129]
	v_mfma_f32_16x16x32_bf16 v[122:125], v[182:185], v[190:193], v[122:125]
	v_mfma_f32_16x16x32_bf16 v[108:111], v[174:177], v[204:207], v[108:111]
	v_mfma_f32_16x16x32_bf16 v[104:107], v[182:185], v[204:207], v[104:107]
	v_mfma_f32_16x16x32_bf16 v[92:95], v[174:177], v[212:215], v[92:95]
	v_mfma_f32_16x16x32_bf16 v[88:91], v[182:185], v[212:215], v[88:91]
	v_mfma_f32_16x16x32_bf16 v[76:79], v[174:177], v[238:241], v[76:79]
	v_mfma_f32_16x16x32_bf16 v[72:75], v[182:185], v[238:241], v[72:75]
	v_mfma_f32_16x16x32_bf16 v[126:129], v[178:181], v[200:203], v[126:129]
	v_mfma_f32_16x16x32_bf16 v[122:125], v[186:189], v[200:203], v[122:125]
	v_mfma_f32_16x16x32_bf16 v[108:111], v[178:181], v[208:211], v[108:111]
	v_mfma_f32_16x16x32_bf16 v[104:107], v[186:189], v[208:211], v[104:107]
	v_mfma_f32_16x16x32_bf16 v[92:95], v[178:181], v[234:237], v[92:95]
	v_mfma_f32_16x16x32_bf16 v[88:91], v[186:189], v[234:237], v[88:91]
	v_mfma_f32_16x16x32_bf16 v[76:79], v[178:181], v[242:245], v[76:79]
	v_mfma_f32_16x16x32_bf16 v[72:75], v[186:189], v[242:245], v[72:75]
	s_setprio 0
	s_barrier
	s_add_i32 s8, s13, s81
	s_nop 0
	s_mov_b32 m0, s8
	ds_read_b128 v[190:193], v169 offset:16384
	ds_read_b128 v[200:203], v169 offset:17408
	ds_read_b128 v[204:207], v169 offset:18432
	ds_read_b128 v[208:211], v169 offset:19456
	ds_read_b128 v[212:215], v169 offset:20480
	ds_read_b128 v[234:237], v169 offset:21504
	ds_read_b128 v[238:241], v169 offset:22528
	ds_read_b128 v[242:245], v169 offset:23552
	global_load_lds_dwordx4 v112, s[94:95]
	s_add_i32 m0, s8, 0x2000
	s_add_u32 s8, s94, 0x40000
	v_lshl_add_u64 v[228:229], s[94:95], 0, v[142:143]
	s_addc_u32 s9, s95, 0
	s_add_i32 s13, s15, s81
	global_load_lds_dwordx4 v142, s[94:95]
	s_nop 0
	s_mov_b32 m0, s13
	s_nop 0
	global_load_lds_dwordx4 v112, s[8:9]
	s_nop 0
	s_add_i32 m0, s13, 0x2000
	s_nop 0
	global_load_lds_dwordx4 v142, s[8:9]
	s_nop 0
	s_mov_b32 m0, s11
	s_nop 0
	global_load_lds_dwordx4 v138, vcc
	s_mov_b32 m0, s19
	s_nop 0
	global_load_lds_dwordx4 v140, vcc
	s_waitcnt vmcnt(8)
	s_waitcnt lgkmcnt(0)
	s_barrier
	s_setprio 1
	v_mfma_f32_16x16x32_bf16 v[68:71], v[150:153], v[190:193], v[68:71]
	v_mfma_f32_16x16x32_bf16 v[64:67], v[158:161], v[190:193], v[64:67]
	v_mfma_f32_16x16x32_bf16 v[52:55], v[150:153], v[204:207], v[52:55]
	v_mfma_f32_16x16x32_bf16 v[48:51], v[158:161], v[204:207], v[48:51]
	v_mfma_f32_16x16x32_bf16 v[36:39], v[150:153], v[212:215], v[36:39]
	v_mfma_f32_16x16x32_bf16 v[32:35], v[158:161], v[212:215], v[32:35]
	v_mfma_f32_16x16x32_bf16 v[20:23], v[150:153], v[238:241], v[20:23]
	v_mfma_f32_16x16x32_bf16 v[16:19], v[158:161], v[238:241], v[16:19]
	v_mfma_f32_16x16x32_bf16 v[68:71], v[154:157], v[200:203], v[68:71]
	v_mfma_f32_16x16x32_bf16 v[64:67], v[170:173], v[200:203], v[64:67]
	v_mfma_f32_16x16x32_bf16 v[52:55], v[154:157], v[208:211], v[52:55]
	v_mfma_f32_16x16x32_bf16 v[48:51], v[170:173], v[208:211], v[48:51]
	v_mfma_f32_16x16x32_bf16 v[36:39], v[154:157], v[234:237], v[36:39]
	v_mfma_f32_16x16x32_bf16 v[32:35], v[170:173], v[234:237], v[32:35]
	v_mfma_f32_16x16x32_bf16 v[20:23], v[154:157], v[242:245], v[20:23]
	v_mfma_f32_16x16x32_bf16 v[16:19], v[170:173], v[242:245], v[16:19]
	v_mfma_f32_16x16x32_bf16 v[60:63], v[174:177], v[190:193], v[60:63]
	v_mfma_f32_16x16x32_bf16 v[56:59], v[182:185], v[190:193], v[56:59]
	v_mfma_f32_16x16x32_bf16 v[44:47], v[174:177], v[204:207], v[44:47]
	v_mfma_f32_16x16x32_bf16 v[40:43], v[182:185], v[204:207], v[40:43]
	v_mfma_f32_16x16x32_bf16 v[28:31], v[174:177], v[212:215], v[28:31]
	v_mfma_f32_16x16x32_bf16 v[24:27], v[182:185], v[212:215], v[24:27]
	v_mfma_f32_16x16x32_bf16 v[12:15], v[174:177], v[238:241], v[12:15]
	v_mfma_f32_16x16x32_bf16 v[8:11], v[182:185], v[238:241], v[8:11]
	v_mfma_f32_16x16x32_bf16 v[60:63], v[178:181], v[200:203], v[60:63]
	v_mfma_f32_16x16x32_bf16 v[56:59], v[186:189], v[200:203], v[56:59]
	v_mfma_f32_16x16x32_bf16 v[44:47], v[178:181], v[208:211], v[44:47]
	v_mfma_f32_16x16x32_bf16 v[40:43], v[186:189], v[208:211], v[40:43]
	v_mfma_f32_16x16x32_bf16 v[28:31], v[178:181], v[234:237], v[28:31]
	v_mfma_f32_16x16x32_bf16 v[24:27], v[186:189], v[234:237], v[24:27]
	v_mfma_f32_16x16x32_bf16 v[12:15], v[178:181], v[242:245], v[12:15]
	v_mfma_f32_16x16x32_bf16 v[8:11], v[186:189], v[242:245], v[8:11]
	s_setprio 0
	s_barrier
; #define PG8_STAGE(bufoff, gbase, voff) do { _Pragma("unroll") for (int _i = 0; _i < 2; ++_i) \
;         __builtin_amdgcn_global_load_lds((const unsigned*)((const char*)(gbase) + (voff)[_i]), (LAS unsigned*)(lds + (bufoff) + ldsw + _i * 8192), 16, 0, 0); } while (0)
; #define PG8_LDA(dst, b, h) do { _Pragma("unroll") for (int m = 0; m < 4; ++m) _Pragma("unroll") for (int k = 0; k < 2; ++k) dst[m][k] = *(const LAS bf16x8*)(lds + PG8_SA(b, h) + aoff + m * 2048 + k * 1024); } while (0)
; #define PG8_LDB(dst, b, h) do { _Pragma("unroll") for (int n = 0; n < 2; ++n) _Pragma("unroll") for (int k = 0; k < 2; ++k) dst[n][k] = *(const LAS bf16x8*)(lds + PG8_SB(b, h) + boff + n * 2048 + k * 1024); } while (0)
; #define PG8_MMA(ai, bj, At, Bt) do { __builtin_amdgcn_s_setprio(1); _Pragma("unroll") for (int m = 0; m < 4; ++m) _Pragma("unroll") for (int n = 0; n < 2; ++n) _Pragma("unroll") for (int k = 0; k < 2; ++k) \
;         acc[ai][bj][m][n] = __builtin_amdgcn_mfma_f32_16x16x32_bf16(Bt[n][k], At[m][k], acc[ai][bj][m][n], 0, 0, 0); __builtin_amdgcn_s_setprio(0); } while (0)
; #define PG8_WAIT_V(n) asm volatile("s_waitcnt vmcnt(" #n ")" ::: "memory")
; #define PG8_WAIT_L(n) asm volatile("s_waitcnt lgkmcnt(" #n ")" ::: "memory")
; #define PG8_BAR __builtin_amdgcn_s_barrier()
; #define PG8_SCHED __builtin_amdgcn_sched_barrier(0)
; template <class Epi>
; __device__ __forceinline__ void gemm_phase(LAS unsigned char* lds, const Gemm g, const StaticOrder& S, const Epi& E, const int tid) {
;     ...
;             PG8_LDB(B0, 1, 0); PG8_LDB(B1, 1, 1); PG8_SCHED; PG8_LDA(At, 1, 0); PG8_STAGE(PG8_SA(0, 1), a2 + hstepA, voffA);
;             PG8_WAIT_V(8); PG8_WAIT_L(0); PG8_BAR; PG8_MMA(0, 0, At, B0); PG8_MMA(0, 1, At, B1); PG8_BAR; PG8_SCHED;
;             PG8_LDA(At, 1, 1); PG8_STAGE(PG8_SB(1, 0), b3, voffB); PG8_STAGE(PG8_SB(1, 1), b3 + hstepB, voffB); PG8_STAGE(PG8_SA(1, 0), a3, voffA);
;             PG8_WAIT_V(8); PG8_WAIT_L(0); PG8_BAR; PG8_MMA(1, 0, At, B0); PG8_MMA(1, 1, At, B1); PG8_BAR; PG8_SCHED;
;         }
;         if (wr == 0) PG8_BAR;
	s_add_i32 s13, 0, 0x18000
	s_add_i32 s31, 0, 0x1c000
	v_add_u32_e32 v170, s13, v167
	v_add_u32_e32 v186, s31, v167
	ds_read_b128 v[150:153], v170
	ds_read_b128 v[154:157], v170 offset:1024
	ds_read_b128 v[158:161], v170 offset:2048
	ds_read_b128 v[170:173], v170 offset:3072
	ds_read_b128 v[174:177], v186
	ds_read_b128 v[178:181], v186 offset:1024
	ds_read_b128 v[182:185], v186 offset:2048
	ds_read_b128 v[186:189], v186 offset:3072
	s_add_u32 s8, vcc_lo, 0x40000
	s_addc_u32 s9, vcc_hi, 0
	s_mov_b32 m0, s98
	s_nop 0
	ds_read_b128 v[190:193], v169 offset:32768
	ds_read_b128 v[200:203], v169 offset:33792
	ds_read_b128 v[204:207], v169 offset:34816
	ds_read_b128 v[208:211], v169 offset:35840
	ds_read_b128 v[212:215], v169 offset:36864
	ds_read_b128 v[234:237], v169 offset:37888
	ds_read_b128 v[238:241], v169 offset:38912
	ds_read_b128 v[242:245], v169 offset:39936
	global_load_lds_dwordx4 v138, s[8:9]
	s_nop 0
	s_mov_b32 m0, s99
	s_nop 0
	global_load_lds_dwordx4 v140, s[8:9]
	s_waitcnt vmcnt(8)
	s_waitcnt lgkmcnt(0)
	s_barrier
	s_setprio 1
	v_mfma_f32_16x16x32_bf16 v[134:137], v[150:153], v[190:193], v[134:137]
	v_mfma_f32_16x16x32_bf16 v[130:133], v[158:161], v[190:193], v[130:133]
	v_mfma_f32_16x16x32_bf16 v[118:121], v[150:153], v[204:207], v[118:121]
	v_mfma_f32_16x16x32_bf16 v[114:117], v[158:161], v[204:207], v[114:117]
	v_mfma_f32_16x16x32_bf16 v[100:103], v[150:153], v[212:215], v[100:103]
	v_mfma_f32_16x16x32_bf16 v[96:99], v[158:161], v[212:215], v[96:99]
	v_mfma_f32_16x16x32_bf16 v[84:87], v[150:153], v[238:241], v[84:87]
	v_mfma_f32_16x16x32_bf16 v[80:83], v[158:161], v[238:241], v[80:83]
	v_mfma_f32_16x16x32_bf16 v[134:137], v[154:157], v[200:203], v[134:137]
	v_mfma_f32_16x16x32_bf16 v[130:133], v[170:173], v[200:203], v[130:133]
	v_mfma_f32_16x16x32_bf16 v[118:121], v[154:157], v[208:211], v[118:121]
	v_mfma_f32_16x16x32_bf16 v[114:117], v[170:173], v[208:211], v[114:117]
	v_mfma_f32_16x16x32_bf16 v[100:103], v[154:157], v[234:237], v[100:103]
	v_mfma_f32_16x16x32_bf16 v[96:99], v[170:173], v[234:237], v[96:99]
	v_mfma_f32_16x16x32_bf16 v[84:87], v[154:157], v[242:245], v[84:87]
	v_mfma_f32_16x16x32_bf16 v[80:83], v[170:173], v[242:245], v[80:83]
	v_mfma_f32_16x16x32_bf16 v[126:129], v[174:177], v[190:193], v[126:129]
	v_mfma_f32_16x16x32_bf16 v[122:125], v[182:185], v[190:193], v[122:125]
	v_mfma_f32_16x16x32_bf16 v[108:111], v[174:177], v[204:207], v[108:111]
	v_mfma_f32_16x16x32_bf16 v[104:107], v[182:185], v[204:207], v[104:107]
	v_mfma_f32_16x16x32_bf16 v[92:95], v[174:177], v[212:215], v[92:95]
	v_mfma_f32_16x16x32_bf16 v[88:91], v[182:185], v[212:215], v[88:91]
	v_mfma_f32_16x16x32_bf16 v[76:79], v[174:177], v[238:241], v[76:79]
	v_mfma_f32_16x16x32_bf16 v[72:75], v[182:185], v[238:241], v[72:75]
	v_mfma_f32_16x16x32_bf16 v[126:129], v[178:181], v[200:203], v[126:129]
	v_mfma_f32_16x16x32_bf16 v[122:125], v[186:189], v[200:203], v[122:125]
	v_mfma_f32_16x16x32_bf16 v[108:111], v[178:181], v[208:211], v[108:111]
	v_mfma_f32_16x16x32_bf16 v[104:107], v[186:189], v[208:211], v[104:107]
	v_mfma_f32_16x16x32_bf16 v[92:95], v[178:181], v[234:237], v[92:95]
	v_mfma_f32_16x16x32_bf16 v[88:91], v[186:189], v[234:237], v[88:91]
	v_mfma_f32_16x16x32_bf16 v[76:79], v[178:181], v[242:245], v[76:79]
	v_mfma_f32_16x16x32_bf16 v[72:75], v[186:189], v[242:245], v[72:75]
	s_setprio 0
	s_barrier
	s_add_i32 s8, s13, s81
	s_add_u32 s100, s94, 0x80
	s_addc_u32 s101, s95, 0
	s_mov_b32 m0, s8
	ds_read_b128 v[190:193], v169 offset:49152
	ds_read_b128 v[200:203], v169 offset:50176
	ds_read_b128 v[204:207], v169 offset:51200
	ds_read_b128 v[208:211], v169 offset:52224
	ds_read_b128 v[212:215], v169 offset:53248
	ds_read_b128 v[234:237], v169 offset:54272
	ds_read_b128 v[238:241], v169 offset:55296
	ds_read_b128 v[242:245], v169 offset:56320
	global_load_lds_dwordx4 v112, s[100:101]
	s_add_i32 m0, s8, 0x2000
	s_add_u32 s8, s94, 0x40080
	v_lshl_add_u64 v[162:163], v[228:229], 0, s[24:25]
	s_addc_u32 s9, s95, 0
	s_add_i32 s13, s31, s81
	global_load_lds_dwordx4 v[162:163], off
	s_nop 0
	s_mov_b32 m0, s13
	s_nop 0
	global_load_lds_dwordx4 v112, s[8:9]
	s_nop 0
	s_add_i32 m0, s13, 0x2000
	s_nop 0
	global_load_lds_dwordx4 v142, s[8:9]
	s_add_u32 s100, vcc_lo, 0x80
	s_addc_u32 s101, vcc_hi, 0
	s_mov_b32 m0, s38
	s_nop 0
	global_load_lds_dwordx4 v138, s[100:101]
	s_add_u32 s100, vcc_lo, 0x80
	s_addc_u32 s101, vcc_hi, 0
	s_mov_b32 m0, s39
	s_nop 0
	global_load_lds_dwordx4 v140, s[100:101]
	s_waitcnt vmcnt(8)
	s_waitcnt lgkmcnt(0)
	s_barrier
	s_setprio 1
	v_mfma_f32_16x16x32_bf16 v[68:71], v[150:153], v[190:193], v[68:71]
	v_mfma_f32_16x16x32_bf16 v[64:67], v[158:161], v[190:193], v[64:67]
	v_mfma_f32_16x16x32_bf16 v[52:55], v[150:153], v[204:207], v[52:55]
	v_mfma_f32_16x16x32_bf16 v[48:51], v[158:161], v[204:207], v[48:51]
	v_mfma_f32_16x16x32_bf16 v[36:39], v[150:153], v[212:215], v[36:39]
	v_mfma_f32_16x16x32_bf16 v[32:35], v[158:161], v[212:215], v[32:35]
	v_mfma_f32_16x16x32_bf16 v[20:23], v[150:153], v[238:241], v[20:23]
	v_mfma_f32_16x16x32_bf16 v[16:19], v[158:161], v[238:241], v[16:19]
	v_mfma_f32_16x16x32_bf16 v[68:71], v[154:157], v[200:203], v[68:71]
	v_mfma_f32_16x16x32_bf16 v[64:67], v[170:173], v[200:203], v[64:67]
	v_mfma_f32_16x16x32_bf16 v[52:55], v[154:157], v[208:211], v[52:55]
	v_mfma_f32_16x16x32_bf16 v[48:51], v[170:173], v[208:211], v[48:51]
	v_mfma_f32_16x16x32_bf16 v[36:39], v[154:157], v[234:237], v[36:39]
	v_mfma_f32_16x16x32_bf16 v[32:35], v[170:173], v[234:237], v[32:35]
	v_mfma_f32_16x16x32_bf16 v[20:23], v[154:157], v[242:245], v[20:23]
	v_mfma_f32_16x16x32_bf16 v[16:19], v[170:173], v[242:245], v[16:19]
	v_mfma_f32_16x16x32_bf16 v[60:63], v[174:177], v[190:193], v[60:63]
	v_mfma_f32_16x16x32_bf16 v[56:59], v[182:185], v[190:193], v[56:59]
	v_mfma_f32_16x16x32_bf16 v[44:47], v[174:177], v[204:207], v[44:47]
	v_mfma_f32_16x16x32_bf16 v[40:43], v[182:185], v[204:207], v[40:43]
	v_mfma_f32_16x16x32_bf16 v[28:31], v[174:177], v[212:215], v[28:31]
	v_mfma_f32_16x16x32_bf16 v[24:27], v[182:185], v[212:215], v[24:27]
	v_mfma_f32_16x16x32_bf16 v[12:15], v[174:177], v[238:241], v[12:15]
	v_mfma_f32_16x16x32_bf16 v[8:11], v[182:185], v[238:241], v[8:11]
	v_mfma_f32_16x16x32_bf16 v[60:63], v[178:181], v[200:203], v[60:63]
	v_mfma_f32_16x16x32_bf16 v[56:59], v[186:189], v[200:203], v[56:59]
	v_mfma_f32_16x16x32_bf16 v[44:47], v[178:181], v[208:211], v[44:47]
	v_mfma_f32_16x16x32_bf16 v[40:43], v[186:189], v[208:211], v[40:43]
	v_mfma_f32_16x16x32_bf16 v[28:31], v[178:181], v[234:237], v[28:31]
	v_mfma_f32_16x16x32_bf16 v[24:27], v[186:189], v[234:237], v[24:27]
	v_mfma_f32_16x16x32_bf16 v[12:15], v[178:181], v[242:245], v[12:15]
	v_mfma_f32_16x16x32_bf16 v[8:11], v[186:189], v[242:245], v[8:11]
	s_setprio 0
	s_barrier
	s_add_i32 s85, s85, 2
	s_add_u32 s40, s40, 0x100
	s_addc_u32 s41, s41, 0
	s_add_u32 s46, s46, 0x100
	s_addc_u32 s57, s57, 0
	s_cmp_gt_u32 s85, 13
	s_cbranch_scc0 .LBB0_268
	s_and_b64 vcc, exec, s[82:83]
	s_cbranch_vccz .LBB0_271
	s_barrier

; #define PG8_STAGE(bufoff, gbase, voff) do { _Pragma("unroll") for (int _i = 0; _i < 2; ++_i) \
;         __builtin_amdgcn_global_load_lds((const unsigned*)((const char*)(gbase) + (voff)[_i]), (LAS unsigned*)(lds + (bufoff) + ldsw + _i * 8192), 16, 0, 0); } while (0)
; #define PG8_LDA(dst, b, h) do { _Pragma("unroll") for (int m = 0; m < 4; ++m) _Pragma("unroll") for (int k = 0; k < 2; ++k) dst[m][k] = *(const LAS bf16x8*)(lds + PG8_SA(b, h) + aoff + m * 2048 + k * 1024); } while (0)
; #define PG8_LDB(dst, b, h) do { _Pragma("unroll") for (int n = 0; n < 2; ++n) _Pragma("unroll") for (int k = 0; k < 2; ++k) dst[n][k] = *(const LAS bf16x8*)(lds + PG8_SB(b, h) + boff + n * 2048 + k * 1024); } while (0)
; #define PG8_MMA(ai, bj, At, Bt) do { __builtin_amdgcn_s_setprio(1); _Pragma("unroll") for (int m = 0; m < 4; ++m) _Pragma("unroll") for (int n = 0; n < 2; ++n) _Pragma("unroll") for (int k = 0; k < 2; ++k) \
;         acc[ai][bj][m][n] = __builtin_amdgcn_mfma_f32_16x16x32_bf16(Bt[n][k], At[m][k], acc[ai][bj][m][n], 0, 0, 0); __builtin_amdgcn_s_setprio(0); } while (0)
; #define PG8_WAIT_V(n) asm volatile("s_waitcnt vmcnt(" #n ")" ::: "memory")
; #define PG8_WAIT_L(n) asm volatile("s_waitcnt lgkmcnt(" #n ")" ::: "memory")
; #define PG8_BAR __builtin_amdgcn_s_barrier()
; template <class Epi>
; __device__ __forceinline__ void gemm_phase(LAS unsigned char* lds, const Gemm g, const StaticOrder& S, const Epi& E, const int tid) {
;     ...
;         for (int t = 0; t < nt; t += 2) {
;             const bool last = (t == nt - 2);
;             const char* a1 = cA + (size_t)(t + 1) * kstep + ((t + 1) >= 8 ? xtra : 0);
;             const char* a2 = last ? nA : cA + (size_t)(t + 2) * kstep + ((t + 2) >= 8 ? xtra : 0); const char* b2 = last ? nB : cB + (size_t)(t + 2) * kstep;
;             const char* a3 = a2 + kstep; const char* b3 = b2 + kstep;
;             PG8_LDB(B0, 0, 0); PG8_LDB(B1, 0, 1); PG8_SCHED; PG8_LDA(At, 0, 0); PG8_STAGE(PG8_SA(1, 1), a1 + hstepA, voffA);
;             PG8_WAIT_V(8); PG8_WAIT_L(0); PG8_BAR; PG8_MMA(0, 0, At, B0); PG8_MMA(0, 1, At, B1); PG8_BAR; PG8_SCHED;
;             PG8_LDA(At, 0, 1); PG8_STAGE(PG8_SB(0, 0), b2, voffB); PG8_STAGE(PG8_SB(0, 1), b2 + hstepB, voffB); PG8_STAGE(PG8_SA(0, 0), a2, voffA);
;             PG8_WAIT_V(8); PG8_WAIT_L(0); PG8_BAR; PG8_MMA(1, 0, At, B0); PG8_MMA(1, 1, At, B1); PG8_BAR; PG8_SCHED;
.LBB0_356:
	s_add_u32 s8, s42, 0xfffc0080
	s_addc_u32 s9, s43, -1
	s_add_i32 s13, 0, 0x10000
	v_add_u32_e32 v168, s13, v161
	v_add_u32_e32 v184, s15, v161
	ds_read_b128 v[150:153], v168
	ds_read_b128 v[154:157], v168 offset:1024
	ds_read_b128 v[164:167], v168 offset:2048
	ds_read_b128 v[168:171], v168 offset:3072
	ds_read_b128 v[172:175], v184
	ds_read_b128 v[176:179], v184 offset:1024
	ds_read_b128 v[180:183], v184 offset:2048
	ds_read_b128 v[184:187], v184 offset:3072
	s_cmp_eq_u32 s97, 12
	s_cselect_b32 s95, s98, s9
	s_cselect_b32 s94, s99, s8
	s_cselect_b32 s93, s83, s96
	s_cselect_b32 s92, vcc_lo, vcc_hi
	s_nop 0
	s_add_i32 m0, s19, 0xc000
	ds_read_b128 v[188:191], v163
	ds_read_b128 v[200:203], v163 offset:1024
	ds_read_b128 v[204:207], v163 offset:2048
	ds_read_b128 v[208:211], v163 offset:3072
	ds_read_b128 v[212:215], v163 offset:4096
	ds_read_b128 v[234:237], v163 offset:5120
	ds_read_b128 v[238:241], v163 offset:6144
	ds_read_b128 v[242:245], v163 offset:7168
	global_load_lds_dwordx4 v146, s[42:43]
	s_nop 0
	s_add_i32 m0, s19, 0xe000
	s_nop 0
	global_load_lds_dwordx4 v148, s[42:43]
	s_waitcnt vmcnt(8)
	s_waitcnt lgkmcnt(0)
	s_barrier
	s_setprio 1
	v_mfma_f32_16x16x32_bf16 v[134:137], v[150:153], v[188:191], v[134:137]
	v_mfma_f32_16x16x32_bf16 v[130:133], v[164:167], v[188:191], v[130:133]
	v_mfma_f32_16x16x32_bf16 v[122:125], v[150:153], v[204:207], v[122:125]
	v_mfma_f32_16x16x32_bf16 v[114:117], v[164:167], v[204:207], v[114:117]
	v_mfma_f32_16x16x32_bf16 v[104:107], v[150:153], v[212:215], v[104:107]
	v_mfma_f32_16x16x32_bf16 v[96:99], v[164:167], v[212:215], v[96:99]
	v_mfma_f32_16x16x32_bf16 v[88:91], v[150:153], v[238:241], v[88:91]
	v_mfma_f32_16x16x32_bf16 v[80:83], v[164:167], v[238:241], v[80:83]
	v_mfma_f32_16x16x32_bf16 v[134:137], v[154:157], v[200:203], v[134:137]
	v_mfma_f32_16x16x32_bf16 v[130:133], v[168:171], v[200:203], v[130:133]
	v_mfma_f32_16x16x32_bf16 v[122:125], v[154:157], v[208:211], v[122:125]
	v_mfma_f32_16x16x32_bf16 v[114:117], v[168:171], v[208:211], v[114:117]
	v_mfma_f32_16x16x32_bf16 v[104:107], v[154:157], v[234:237], v[104:107]
	v_mfma_f32_16x16x32_bf16 v[96:99], v[168:171], v[234:237], v[96:99]
	v_mfma_f32_16x16x32_bf16 v[88:91], v[154:157], v[242:245], v[88:91]
	v_mfma_f32_16x16x32_bf16 v[80:83], v[168:171], v[242:245], v[80:83]
	v_mfma_f32_16x16x32_bf16 v[126:129], v[172:175], v[188:191], v[126:129]
	v_mfma_f32_16x16x32_bf16 v[118:121], v[180:183], v[188:191], v[118:121]
	v_mfma_f32_16x16x32_bf16 v[108:111], v[172:175], v[204:207], v[108:111]
	v_mfma_f32_16x16x32_bf16 v[100:103], v[180:183], v[204:207], v[100:103]
	v_mfma_f32_16x16x32_bf16 v[92:95], v[172:175], v[212:215], v[92:95]
	v_mfma_f32_16x16x32_bf16 v[84:87], v[180:183], v[212:215], v[84:87]
	v_mfma_f32_16x16x32_bf16 v[76:79], v[172:175], v[238:241], v[76:79]
	v_mfma_f32_16x16x32_bf16 v[72:75], v[180:183], v[238:241], v[72:75]
	v_mfma_f32_16x16x32_bf16 v[126:129], v[176:179], v[200:203], v[126:129]
	v_mfma_f32_16x16x32_bf16 v[118:121], v[184:187], v[200:203], v[118:121]
	v_mfma_f32_16x16x32_bf16 v[108:111], v[176:179], v[208:211], v[108:111]
	v_mfma_f32_16x16x32_bf16 v[100:103], v[184:187], v[208:211], v[100:103]
	v_mfma_f32_16x16x32_bf16 v[92:95], v[176:179], v[234:237], v[92:95]
	v_mfma_f32_16x16x32_bf16 v[84:87], v[184:187], v[234:237], v[84:87]
	v_mfma_f32_16x16x32_bf16 v[76:79], v[176:179], v[242:245], v[76:79]
	v_mfma_f32_16x16x32_bf16 v[72:75], v[184:187], v[242:245], v[72:75]
	s_setprio 0
	s_barrier
	s_add_i32 s8, s13, s17
	s_nop 0
	s_mov_b32 m0, s8
	ds_read_b128 v[188:191], v163 offset:16384
	ds_read_b128 v[200:203], v163 offset:17408
	ds_read_b128 v[204:207], v163 offset:18432
	ds_read_b128 v[208:211], v163 offset:19456
	ds_read_b128 v[212:215], v163 offset:20480
	ds_read_b128 v[234:237], v163 offset:21504
	ds_read_b128 v[238:241], v163 offset:22528
	ds_read_b128 v[242:245], v163 offset:23552
	global_load_lds_dwordx4 v112, s[92:93]
	s_add_i32 m0, s8, 0x2000
	s_add_u32 s8, s92, 0x40000
	v_lshl_add_u64 v[246:247], s[92:93], 0, v[142:143]
	s_addc_u32 s9, s93, 0
	s_add_i32 s13, s15, s17
	global_load_lds_dwordx4 v142, s[92:93]
	s_nop 0
	s_mov_b32 m0, s13
	s_nop 0
	global_load_lds_dwordx4 v112, s[8:9]
	s_nop 0
	s_add_i32 m0, s13, 0x2000
	s_nop 0
	global_load_lds_dwordx4 v142, s[8:9]
	s_nop 0
	s_mov_b32 m0, s19
	s_nop 0
	global_load_lds_dwordx4 v138, s[94:95]
	s_mov_b32 m0, s23
	s_nop 0
	global_load_lds_dwordx4 v140, s[94:95]
	s_waitcnt vmcnt(8)
	s_waitcnt lgkmcnt(0)
	s_barrier
	s_setprio 1
	v_mfma_f32_16x16x32_bf16 v[68:71], v[150:153], v[188:191], v[68:71]
	v_mfma_f32_16x16x32_bf16 v[64:67], v[164:167], v[188:191], v[64:67]
	v_mfma_f32_16x16x32_bf16 v[56:59], v[150:153], v[204:207], v[56:59]
	v_mfma_f32_16x16x32_bf16 v[48:51], v[164:167], v[204:207], v[48:51]
	v_mfma_f32_16x16x32_bf16 v[40:43], v[150:153], v[212:215], v[40:43]
	v_mfma_f32_16x16x32_bf16 v[32:35], v[164:167], v[212:215], v[32:35]
	v_mfma_f32_16x16x32_bf16 v[24:27], v[150:153], v[238:241], v[24:27]
	v_mfma_f32_16x16x32_bf16 v[16:19], v[164:167], v[238:241], v[16:19]
	v_mfma_f32_16x16x32_bf16 v[68:71], v[154:157], v[200:203], v[68:71]
	v_mfma_f32_16x16x32_bf16 v[64:67], v[168:171], v[200:203], v[64:67]
	v_mfma_f32_16x16x32_bf16 v[56:59], v[154:157], v[208:211], v[56:59]
	v_mfma_f32_16x16x32_bf16 v[48:51], v[168:171], v[208:211], v[48:51]
	v_mfma_f32_16x16x32_bf16 v[40:43], v[154:157], v[234:237], v[40:43]
	v_mfma_f32_16x16x32_bf16 v[32:35], v[168:171], v[234:237], v[32:35]
	v_mfma_f32_16x16x32_bf16 v[24:27], v[154:157], v[242:245], v[24:27]
	v_mfma_f32_16x16x32_bf16 v[16:19], v[168:171], v[242:245], v[16:19]
	v_mfma_f32_16x16x32_bf16 v[60:63], v[172:175], v[188:191], v[60:63]
	v_mfma_f32_16x16x32_bf16 v[52:55], v[180:183], v[188:191], v[52:55]
	v_mfma_f32_16x16x32_bf16 v[44:47], v[172:175], v[204:207], v[44:47]
	v_mfma_f32_16x16x32_bf16 v[36:39], v[180:183], v[204:207], v[36:39]
	v_mfma_f32_16x16x32_bf16 v[28:31], v[172:175], v[212:215], v[28:31]
	v_mfma_f32_16x16x32_bf16 v[20:23], v[180:183], v[212:215], v[20:23]
	v_mfma_f32_16x16x32_bf16 v[12:15], v[172:175], v[238:241], v[12:15]
	v_mfma_f32_16x16x32_bf16 v[8:11], v[180:183], v[238:241], v[8:11]
	v_mfma_f32_16x16x32_bf16 v[60:63], v[176:179], v[200:203], v[60:63]
	v_mfma_f32_16x16x32_bf16 v[52:55], v[184:187], v[200:203], v[52:55]
	v_mfma_f32_16x16x32_bf16 v[44:47], v[176:179], v[208:211], v[44:47]
	v_mfma_f32_16x16x32_bf16 v[36:39], v[184:187], v[208:211], v[36:39]
	v_mfma_f32_16x16x32_bf16 v[28:31], v[176:179], v[234:237], v[28:31]
	v_mfma_f32_16x16x32_bf16 v[20:23], v[184:187], v[234:237], v[20:23]
	v_mfma_f32_16x16x32_bf16 v[12:15], v[176:179], v[242:245], v[12:15]
	v_mfma_f32_16x16x32_bf16 v[8:11], v[184:187], v[242:245], v[8:11]
	s_setprio 0
	s_barrier
; #define PG8_STAGE(bufoff, gbase, voff) do { _Pragma("unroll") for (int _i = 0; _i < 2; ++_i) \
;         __builtin_amdgcn_global_load_lds((const unsigned*)((const char*)(gbase) + (voff)[_i]), (LAS unsigned*)(lds + (bufoff) + ldsw + _i * 8192), 16, 0, 0); } while (0)
; #define PG8_LDA(dst, b, h) do { _Pragma("unroll") for (int m = 0; m < 4; ++m) _Pragma("unroll") for (int k = 0; k < 2; ++k) dst[m][k] = *(const LAS bf16x8*)(lds + PG8_SA(b, h) + aoff + m * 2048 + k * 1024); } while (0)
; #define PG8_LDB(dst, b, h) do { _Pragma("unroll") for (int n = 0; n < 2; ++n) _Pragma("unroll") for (int k = 0; k < 2; ++k) dst[n][k] = *(const LAS bf16x8*)(lds + PG8_SB(b, h) + boff + n * 2048 + k * 1024); } while (0)
; #define PG8_MMA(ai, bj, At, Bt) do { __builtin_amdgcn_s_setprio(1); _Pragma("unroll") for (int m = 0; m < 4; ++m) _Pragma("unroll") for (int n = 0; n < 2; ++n) _Pragma("unroll") for (int k = 0; k < 2; ++k) \
;         acc[ai][bj][m][n] = __builtin_amdgcn_mfma_f32_16x16x32_bf16(Bt[n][k], At[m][k], acc[ai][bj][m][n], 0, 0, 0); __builtin_amdgcn_s_setprio(0); } while (0)
; #define PG8_WAIT_V(n) asm volatile("s_waitcnt vmcnt(" #n ")" ::: "memory")
; #define PG8_WAIT_L(n) asm volatile("s_waitcnt lgkmcnt(" #n ")" ::: "memory")
; #define PG8_BAR __builtin_amdgcn_s_barrier()
; #define PG8_SCHED __builtin_amdgcn_sched_barrier(0)
; template <class Epi>
; __device__ __forceinline__ void gemm_phase(LAS unsigned char* lds, const Gemm g, const StaticOrder& S, const Epi& E, const int tid) {
;     ...
;             PG8_LDB(B0, 1, 0); PG8_LDB(B1, 1, 1); PG8_SCHED; PG8_LDA(At, 1, 0); PG8_STAGE(PG8_SA(0, 1), a2 + hstepA, voffA);
;             PG8_WAIT_V(8); PG8_WAIT_L(0); PG8_BAR; PG8_MMA(0, 0, At, B0); PG8_MMA(0, 1, At, B1); PG8_BAR; PG8_SCHED;
;             PG8_LDA(At, 1, 1); PG8_STAGE(PG8_SB(1, 0), b3, voffB); PG8_STAGE(PG8_SB(1, 1), b3 + hstepB, voffB); PG8_STAGE(PG8_SA(1, 0), a3, voffA);
;             PG8_WAIT_V(8); PG8_WAIT_L(0); PG8_BAR; PG8_MMA(1, 0, At, B0); PG8_MMA(1, 1, At, B1); PG8_BAR; PG8_SCHED;
;         }
;         if (wr == 0) PG8_BAR;
	s_add_i32 s13, 0, 0x18000
	s_add_i32 s31, 0, 0x1c000
	v_add_u32_e32 v168, s13, v161
	v_add_u32_e32 v184, s31, v161
	ds_read_b128 v[150:153], v168
	ds_read_b128 v[154:157], v168 offset:1024
	ds_read_b128 v[164:167], v168 offset:2048
	ds_read_b128 v[168:171], v168 offset:3072
	ds_read_b128 v[172:175], v184
	ds_read_b128 v[176:179], v184 offset:1024
	ds_read_b128 v[180:183], v184 offset:2048
	ds_read_b128 v[184:187], v184 offset:3072
	s_add_u32 s8, s94, 0x40000
	s_addc_u32 s9, s95, 0
	s_mov_b32 m0, s28
	s_nop 0
	ds_read_b128 v[188:191], v163 offset:32768
	ds_read_b128 v[200:203], v163 offset:33792
	ds_read_b128 v[204:207], v163 offset:34816
	ds_read_b128 v[208:211], v163 offset:35840
	ds_read_b128 v[212:215], v163 offset:36864
	ds_read_b128 v[234:237], v163 offset:37888
	ds_read_b128 v[238:241], v163 offset:38912
	ds_read_b128 v[242:245], v163 offset:39936
	global_load_lds_dwordx4 v138, s[8:9]
	s_nop 0
	s_mov_b32 m0, s30
	s_nop 0
	global_load_lds_dwordx4 v140, s[8:9]
	s_waitcnt vmcnt(8)
	s_waitcnt lgkmcnt(0)
	s_barrier
	s_setprio 1
	v_mfma_f32_16x16x32_bf16 v[134:137], v[150:153], v[188:191], v[134:137]
	v_mfma_f32_16x16x32_bf16 v[130:133], v[164:167], v[188:191], v[130:133]
	v_mfma_f32_16x16x32_bf16 v[122:125], v[150:153], v[204:207], v[122:125]
	v_mfma_f32_16x16x32_bf16 v[114:117], v[164:167], v[204:207], v[114:117]
	v_mfma_f32_16x16x32_bf16 v[104:107], v[150:153], v[212:215], v[104:107]
	v_mfma_f32_16x16x32_bf16 v[96:99], v[164:167], v[212:215], v[96:99]
	v_mfma_f32_16x16x32_bf16 v[88:91], v[150:153], v[238:241], v[88:91]
	v_mfma_f32_16x16x32_bf16 v[80:83], v[164:167], v[238:241], v[80:83]
	v_mfma_f32_16x16x32_bf16 v[134:137], v[154:157], v[200:203], v[134:137]
	v_mfma_f32_16x16x32_bf16 v[130:133], v[168:171], v[200:203], v[130:133]
	v_mfma_f32_16x16x32_bf16 v[122:125], v[154:157], v[208:211], v[122:125]
	v_mfma_f32_16x16x32_bf16 v[114:117], v[168:171], v[208:211], v[114:117]
	v_mfma_f32_16x16x32_bf16 v[104:107], v[154:157], v[234:237], v[104:107]
	v_mfma_f32_16x16x32_bf16 v[96:99], v[168:171], v[234:237], v[96:99]
	v_mfma_f32_16x16x32_bf16 v[88:91], v[154:157], v[242:245], v[88:91]
	v_mfma_f32_16x16x32_bf16 v[80:83], v[168:171], v[242:245], v[80:83]
	v_mfma_f32_16x16x32_bf16 v[126:129], v[172:175], v[188:191], v[126:129]
	v_mfma_f32_16x16x32_bf16 v[118:121], v[180:183], v[188:191], v[118:121]
	v_mfma_f32_16x16x32_bf16 v[108:111], v[172:175], v[204:207], v[108:111]
	v_mfma_f32_16x16x32_bf16 v[100:103], v[180:183], v[204:207], v[100:103]
	v_mfma_f32_16x16x32_bf16 v[92:95], v[172:175], v[212:215], v[92:95]
	v_mfma_f32_16x16x32_bf16 v[84:87], v[180:183], v[212:215], v[84:87]
	v_mfma_f32_16x16x32_bf16 v[76:79], v[172:175], v[238:241], v[76:79]
	v_mfma_f32_16x16x32_bf16 v[72:75], v[180:183], v[238:241], v[72:75]
	v_mfma_f32_16x16x32_bf16 v[126:129], v[176:179], v[200:203], v[126:129]
	v_mfma_f32_16x16x32_bf16 v[118:121], v[184:187], v[200:203], v[118:121]
	v_mfma_f32_16x16x32_bf16 v[108:111], v[176:179], v[208:211], v[108:111]
	v_mfma_f32_16x16x32_bf16 v[100:103], v[184:187], v[208:211], v[100:103]
	v_mfma_f32_16x16x32_bf16 v[92:95], v[176:179], v[234:237], v[92:95]
	v_mfma_f32_16x16x32_bf16 v[84:87], v[184:187], v[234:237], v[84:87]
	v_mfma_f32_16x16x32_bf16 v[76:79], v[176:179], v[242:245], v[76:79]
	v_mfma_f32_16x16x32_bf16 v[72:75], v[184:187], v[242:245], v[72:75]
	s_setprio 0
	s_barrier
	s_add_i32 s8, s13, s17
	s_add_u32 s100, s92, 0x80
	s_addc_u32 s101, s93, 0
	s_mov_b32 m0, s8
	ds_read_b128 v[188:191], v163 offset:49152
	ds_read_b128 v[200:203], v163 offset:50176
	ds_read_b128 v[204:207], v163 offset:51200
	ds_read_b128 v[208:211], v163 offset:52224
	ds_read_b128 v[212:215], v163 offset:53248
	ds_read_b128 v[234:237], v163 offset:54272
	ds_read_b128 v[238:241], v163 offset:55296
	ds_read_b128 v[242:245], v163 offset:56320
	global_load_lds_dwordx4 v112, s[100:101]
	s_add_i32 m0, s8, 0x2000
	s_add_u32 s8, s92, 0x40080
	v_lshl_add_u64 v[192:193], v[246:247], 0, s[24:25]
	s_addc_u32 s9, s93, 0
	s_add_i32 s13, s31, s17
	global_load_lds_dwordx4 v[192:193], off
	s_nop 0
	s_mov_b32 m0, s13
	s_nop 0
	global_load_lds_dwordx4 v112, s[8:9]
	s_nop 0
	s_add_i32 m0, s13, 0x2000
	s_nop 0
	global_load_lds_dwordx4 v142, s[8:9]
	s_add_u32 s100, s94, 0x80
	s_addc_u32 s101, s95, 0
	s_mov_b32 m0, s36
	s_nop 0
	global_load_lds_dwordx4 v138, s[100:101]
	s_add_u32 s100, s94, 0x80
	s_addc_u32 s101, s95, 0
	s_mov_b32 m0, s37
	s_nop 0
	global_load_lds_dwordx4 v140, s[100:101]
	s_waitcnt vmcnt(8)
	s_waitcnt lgkmcnt(0)
	s_barrier
	s_setprio 1
	v_mfma_f32_16x16x32_bf16 v[68:71], v[150:153], v[188:191], v[68:71]
	v_mfma_f32_16x16x32_bf16 v[64:67], v[164:167], v[188:191], v[64:67]
	v_mfma_f32_16x16x32_bf16 v[56:59], v[150:153], v[204:207], v[56:59]
	v_mfma_f32_16x16x32_bf16 v[48:51], v[164:167], v[204:207], v[48:51]
	v_mfma_f32_16x16x32_bf16 v[40:43], v[150:153], v[212:215], v[40:43]
	v_mfma_f32_16x16x32_bf16 v[32:35], v[164:167], v[212:215], v[32:35]
	v_mfma_f32_16x16x32_bf16 v[24:27], v[150:153], v[238:241], v[24:27]
	v_mfma_f32_16x16x32_bf16 v[16:19], v[164:167], v[238:241], v[16:19]
	v_mfma_f32_16x16x32_bf16 v[68:71], v[154:157], v[200:203], v[68:71]
	v_mfma_f32_16x16x32_bf16 v[64:67], v[168:171], v[200:203], v[64:67]
	v_mfma_f32_16x16x32_bf16 v[56:59], v[154:157], v[208:211], v[56:59]
	v_mfma_f32_16x16x32_bf16 v[48:51], v[168:171], v[208:211], v[48:51]
	v_mfma_f32_16x16x32_bf16 v[40:43], v[154:157], v[234:237], v[40:43]
	v_mfma_f32_16x16x32_bf16 v[32:35], v[168:171], v[234:237], v[32:35]
	v_mfma_f32_16x16x32_bf16 v[24:27], v[154:157], v[242:245], v[24:27]
	v_mfma_f32_16x16x32_bf16 v[16:19], v[168:171], v[242:245], v[16:19]
	v_mfma_f32_16x16x32_bf16 v[60:63], v[172:175], v[188:191], v[60:63]
	v_mfma_f32_16x16x32_bf16 v[52:55], v[180:183], v[188:191], v[52:55]
	v_mfma_f32_16x16x32_bf16 v[44:47], v[172:175], v[204:207], v[44:47]
	v_mfma_f32_16x16x32_bf16 v[36:39], v[180:183], v[204:207], v[36:39]
	v_mfma_f32_16x16x32_bf16 v[28:31], v[172:175], v[212:215], v[28:31]
	v_mfma_f32_16x16x32_bf16 v[20:23], v[180:183], v[212:215], v[20:23]
	v_mfma_f32_16x16x32_bf16 v[12:15], v[172:175], v[238:241], v[12:15]
	v_mfma_f32_16x16x32_bf16 v[8:11], v[180:183], v[238:241], v[8:11]
	v_mfma_f32_16x16x32_bf16 v[60:63], v[176:179], v[200:203], v[60:63]
	v_mfma_f32_16x16x32_bf16 v[52:55], v[184:187], v[200:203], v[52:55]
	v_mfma_f32_16x16x32_bf16 v[44:47], v[176:179], v[208:211], v[44:47]
	v_mfma_f32_16x16x32_bf16 v[36:39], v[184:187], v[208:211], v[36:39]
	v_mfma_f32_16x16x32_bf16 v[28:31], v[176:179], v[234:237], v[28:31]
	v_mfma_f32_16x16x32_bf16 v[20:23], v[184:187], v[234:237], v[20:23]
	v_mfma_f32_16x16x32_bf16 v[12:15], v[176:179], v[242:245], v[12:15]
	v_mfma_f32_16x16x32_bf16 v[8:11], v[184:187], v[242:245], v[8:11]
	s_setprio 0
	s_barrier
	s_add_i32 s97, s97, 2
	s_add_u32 s42, s42, 0x100
	s_addc_u32 s43, s43, 0
	s_add_u32 vcc_hi, vcc_hi, 0x100
	s_addc_u32 s96, s96, 0
	s_cmp_gt_u32 s97, 13
	s_cbranch_scc0 .LBB0_356
	s_and_b64 vcc, exec, s[80:81]
	s_cbranch_vccz .LBB0_359
	s_barrier
